# pre_phase part B and LoRA epilogue: waits that only covered earlier stores replaced by nops (loads still waited), on top of v66
# speedup vs baseline: 1.0025x; 1.0025x over previous
.LBB0_677:
	s_add_i32 s46, s46, 7
	s_mul_hi_i32 s57, s46, 0x1980000
	s_andn2_b64 vcc, exec, s[26:27]
	s_add_i32 s54, s54, 0xb280000
	s_cbranch_vccnz .LBB0_679
	s_nop 0
	v_add_f32_e32 v170, v170, v126
	v_add_f32_e32 v171, v171, v127
	v_mul_f32_e32 v170, 0xbfb8aa3b, v170
	v_mul_f32_e32 v171, 0xbfb8aa3b, v171
	v_exp_f32_e32 v170, v170
	v_exp_f32_e32 v171, v171
	v_add_f32_e32 v174, v174, v134
	v_add_f32_e32 v175, v175, v135
	v_add_f32_e32 v176, v176, v136
	v_add_f32_e32 v177, v177, v137
	v_add_f32_e32 v172, v172, v128
	v_add_f32_e32 v173, v173, v129
	v_mul_f32_e32 v174, 0xbfb8aa3b, v174
	v_mul_f32_e32 v175, 0xbfb8aa3b, v175
	v_mul_f32_e32 v176, 0xbfb8aa3b, v176
	v_mul_f32_e32 v177, 0xbfb8aa3b, v177
	v_mul_f32_e32 v172, 0xbfb8aa3b, v172
	v_mul_f32_e32 v173, 0xbfb8aa3b, v173
	v_exp_f32_e32 v174, v174
	v_exp_f32_e32 v175, v175
	v_exp_f32_e32 v176, v176
	v_exp_f32_e32 v177, v177
	v_exp_f32_e32 v172, v172
	v_exp_f32_e32 v173, v173
	v_add_f32_e32 v170, 1.0, v170
	v_add_f32_e32 v171, 1.0, v171
	v_rcp_f32_e32 v170, v170
	v_rcp_f32_e32 v171, v171
	v_add_f32_e32 v174, 1.0, v174
	v_add_f32_e32 v175, 1.0, v175
	v_add_f32_e32 v176, 1.0, v176
	v_add_f32_e32 v177, 1.0, v177
	v_add_f32_e32 v172, 1.0, v172
	v_add_f32_e32 v173, 1.0, v173
	v_rcp_f32_e32 v174, v174
	v_rcp_f32_e32 v175, v175
	v_rcp_f32_e32 v176, v176
	v_rcp_f32_e32 v177, v177
	v_rcp_f32_e32 v172, v172
	v_rcp_f32_e32 v173, v173
	v_mul_f32_e32 v170, 0xbf1b4598, v170
	v_mul_f32_e32 v171, 0xbf1b4598, v171
	v_mul_f32_e32 v170, 0x3fb8aa3b, v170
	v_mul_f32_e32 v171, 0x3fb8aa3b, v171
	v_exp_f32_e32 v170, v170
	v_exp_f32_e32 v171, v171
	v_mul_f32_e32 v174, 0xbf1b4598, v174
	v_mul_f32_e32 v175, 0xbf1b4598, v175
	v_mul_f32_e32 v176, 0xbf1b4598, v176
	v_mul_f32_e32 v177, 0xbf1b4598, v177
	v_mul_f32_e32 v172, 0xbf1b4598, v172
	v_mul_f32_e32 v173, 0xbf1b4598, v173
	v_mul_f32_e32 v174, 0x3fb8aa3b, v174
	v_mul_f32_e32 v175, 0x3fb8aa3b, v175
	v_mul_f32_e32 v176, 0x3fb8aa3b, v176
	v_mul_f32_e32 v177, 0x3fb8aa3b, v177
	v_mul_f32_e32 v172, 0x3fb8aa3b, v172
	v_mul_f32_e32 v173, 0x3fb8aa3b, v173
	v_exp_f32_e32 v174, v174
	v_exp_f32_e32 v175, v175
	v_exp_f32_e32 v176, v176
	v_exp_f32_e32 v177, v177
	v_exp_f32_e32 v172, v172
	v_exp_f32_e32 v173, v173
	s_add_u32 s26, s18, s54
	v_sub_f32_e32 v170, 1.0, v170
	v_sub_f32_e32 v171, 1.0, v171
	s_addc_u32 s27, s19, s57
	v_cvt_pk_bf16_f32 v180, v170, v171
	v_mov_b64_e32 v[170:171], s[26:27]
	v_mad_i64_i32 v[204:205], s[26:27], v219, s3, v[170:171]
	v_sub_f32_e32 v174, 1.0, v174
	v_sub_f32_e32 v175, 1.0, v175
	v_sub_f32_e32 v176, 1.0, v176
	v_sub_f32_e32 v177, 1.0, v177
	v_sub_f32_e32 v172, 1.0, v172
	v_sub_f32_e32 v173, 1.0, v173
	v_cvt_pk_bf16_f32 v178, v174, v175
	v_cvt_pk_bf16_f32 v179, v176, v177
	v_cvt_pk_bf16_f32 v181, v172, v173

.LBB0_686:
	s_and_b64 vcc, exec, s[24:25]
	s_cbranch_vccz .LBB0_688
	s_nop 0
	v_add_f32_e32 v170, v166, v134
	v_mul_f32_e32 v170, 0xbfb8aa3b, v170
	v_add_f32_e32 v171, v167, v135
	v_exp_f32_e32 v170, v170
	v_mul_f32_e32 v171, 0xbfb8aa3b, v171
	v_exp_f32_e32 v171, v171
	v_add_f32_e32 v172, v169, v137
	v_add_f32_e32 v170, 1.0, v170
	v_rcp_f32_e32 v177, v170
	v_add_f32_e32 v170, 1.0, v171
	v_add_f32_e32 v171, v168, v136
	v_mul_f32_e32 v171, 0xbfb8aa3b, v171
	v_exp_f32_e32 v171, v171
	v_mul_f32_e32 v172, 0xbfb8aa3b, v172
	v_exp_f32_e32 v172, v172
	v_rcp_f32_e32 v178, v170
	v_add_f32_e32 v170, 1.0, v171
	v_add_f32_e32 v171, v162, v126
	v_rcp_f32_e32 v179, v170
	v_add_f32_e32 v170, 1.0, v172
	v_mul_f32_e32 v171, 0xbfb8aa3b, v171
	v_add_f32_e32 v172, v163, v127
	v_exp_f32_e32 v171, v171
	v_mul_f32_e32 v172, 0xbfb8aa3b, v172
	v_exp_f32_e32 v172, v172
	v_rcp_f32_e32 v180, v170
	v_add_f32_e32 v170, 1.0, v171
	v_add_f32_e32 v171, v164, v128
	v_rcp_f32_e32 v181, v170
	v_add_f32_e32 v170, 1.0, v172
	v_mul_f32_e32 v171, 0xbfb8aa3b, v171
	v_add_f32_e32 v172, v165, v129
	v_exp_f32_e32 v171, v171
	v_mul_f32_e32 v172, 0xbfb8aa3b, v172
	v_exp_f32_e32 v172, v172
	v_rcp_f32_e32 v204, v170
	v_add_f32_e32 v170, 1.0, v171
	v_rcp_f32_e32 v205, v170
	v_add_f32_e32 v170, 1.0, v172
	v_rcp_f32_e32 v210, v170
	v_lshlrev_b32_e32 v170, 16, v74
	v_and_b32_e32 v171, 0xffff0000, v74
	v_lshlrev_b32_e32 v172, 16, v75
	v_lshlrev_b32_e32 v174, 16, v76
	v_and_b32_e32 v175, 0xffff0000, v76
	s_add_u32 s24, s18, s56
	v_and_b32_e32 v173, 0xffff0000, v75
	v_mul_f32_e32 v170, v177, v170
	v_mul_f32_e32 v171, v178, v171
	v_mul_f32_e32 v172, v179, v172
	v_mul_f32_e32 v174, v181, v174
	v_mul_f32_e32 v175, v204, v175
	s_addc_u32 s25, s19, s77
	v_mul_f32_e32 v173, v180, v173
	v_cvt_pk_bf16_f32 v170, v170, v171
	v_cvt_pk_bf16_f32 v171, v172, v173
	v_cvt_pk_bf16_f32 v172, v174, v175
	v_mov_b64_e32 v[174:175], s[24:25]
	v_mad_i64_i32 v[174:175], s[24:25], v176, s3, v[174:175]
	v_lshlrev_b32_e32 v211, 16, v77
	v_and_b32_e32 v212, 0xffff0000, v77
	v_lshl_add_u64 v[174:175], v[198:199], 1, v[174:175]
	v_add_f32_e32 v177, -1.0, v177
	v_mul_f32_e32 v211, v205, v211
	v_mul_f32_e32 v212, v210, v212
	v_cvt_pk_bf16_f32 v173, v211, v212
	global_store_dwordx4 v[174:175], v[170:173], off
	v_fma_f32 v177, v142, v177, 1.0
	v_lshlrev_b32_e32 v174, 16, v72
	v_lshlrev_b32_e32 v170, 16, v70
	v_mul_f32_e32 v170, v177, v170
	v_add_f32_e32 v177, -1.0, v178
	v_and_b32_e32 v171, 0xffff0000, v70
	v_fma_f32 v177, v143, v177, 1.0
	v_mul_f32_e32 v171, v177, v171
	v_add_f32_e32 v177, -1.0, v179
	v_lshlrev_b32_e32 v172, 16, v71
	v_fma_f32 v177, v144, v177, 1.0
	v_mul_f32_e32 v172, v177, v172
	v_add_f32_e32 v177, -1.0, v180
	v_and_b32_e32 v173, 0xffff0000, v71
	v_fma_f32 v177, v145, v177, 1.0
	v_mul_f32_e32 v173, v177, v173
	v_add_f32_e32 v177, -1.0, v181
	v_fma_f32 v177, v138, v177, 1.0
	v_mul_f32_e32 v174, v177, v174
	v_add_f32_e32 v177, -1.0, v204
	v_and_b32_e32 v175, 0xffff0000, v72
	v_fma_f32 v177, v139, v177, 1.0
	s_add_u32 s24, s18, s76
	v_mul_f32_e32 v175, v177, v175
	s_addc_u32 s25, s19, s86
	v_add_f32_e32 v177, -1.0, v205
	v_add_f32_e32 v178, -1.0, v210
	v_cvt_pk_bf16_f32 v170, v170, v171
	v_cvt_pk_bf16_f32 v171, v172, v173
	v_cvt_pk_bf16_f32 v172, v174, v175
	v_mov_b64_e32 v[174:175], s[24:25]
	v_lshlrev_b32_e32 v211, 16, v73
	v_and_b32_e32 v212, 0xffff0000, v73
	v_fma_f32 v177, v140, v177, 1.0
	v_fma_f32 v178, v141, v178, 1.0
	v_mad_i64_i32 v[174:175], s[24:25], v176, s3, v[174:175]
	v_mul_f32_e32 v177, v177, v211
	v_mul_f32_e32 v178, v178, v212
	v_cvt_pk_bf16_f32 v173, v177, v178

.LBB0_689:
	s_andn2_b64 vcc, exec, s[26:27]
	s_cbranch_vccnz .LBB0_691
	s_nop 0
	v_add_f32_e32 v162, v162, v126
	v_add_f32_e32 v163, v163, v127
	v_mul_f32_e32 v162, 0xbfb8aa3b, v162
	v_mul_f32_e32 v163, 0xbfb8aa3b, v163
	v_exp_f32_e32 v162, v162
	v_exp_f32_e32 v163, v163
	v_add_f32_e32 v166, v166, v134
	v_add_f32_e32 v167, v167, v135
	v_add_f32_e32 v168, v168, v136
	v_add_f32_e32 v169, v169, v137
	v_add_f32_e32 v164, v164, v128
	v_add_f32_e32 v165, v165, v129
	v_mul_f32_e32 v166, 0xbfb8aa3b, v166
	v_mul_f32_e32 v167, 0xbfb8aa3b, v167
	v_mul_f32_e32 v168, 0xbfb8aa3b, v168
	v_mul_f32_e32 v169, 0xbfb8aa3b, v169
	v_mul_f32_e32 v164, 0xbfb8aa3b, v164
	v_mul_f32_e32 v165, 0xbfb8aa3b, v165
	v_exp_f32_e32 v166, v166
	v_exp_f32_e32 v167, v167
	v_exp_f32_e32 v168, v168
	v_exp_f32_e32 v169, v169
	v_exp_f32_e32 v164, v164
	v_exp_f32_e32 v165, v165
	v_add_f32_e32 v162, 1.0, v162
	v_add_f32_e32 v163, 1.0, v163
	v_rcp_f32_e32 v162, v162
	v_rcp_f32_e32 v163, v163
	v_add_f32_e32 v166, 1.0, v166
	v_add_f32_e32 v167, 1.0, v167
	v_add_f32_e32 v168, 1.0, v168
	v_add_f32_e32 v169, 1.0, v169
	v_add_f32_e32 v164, 1.0, v164
	v_add_f32_e32 v165, 1.0, v165
	v_rcp_f32_e32 v166, v166
	v_rcp_f32_e32 v167, v167
	v_rcp_f32_e32 v168, v168
	v_rcp_f32_e32 v169, v169
	v_rcp_f32_e32 v164, v164
	v_rcp_f32_e32 v165, v165
	v_mul_f32_e32 v162, 0xbf1b4598, v162
	v_mul_f32_e32 v163, 0xbf1b4598, v163
	v_mul_f32_e32 v162, 0x3fb8aa3b, v162
	v_mul_f32_e32 v163, 0x3fb8aa3b, v163
	v_exp_f32_e32 v162, v162
	v_exp_f32_e32 v163, v163
	v_mul_f32_e32 v166, 0xbf1b4598, v166
	v_mul_f32_e32 v167, 0xbf1b4598, v167
	v_mul_f32_e32 v168, 0xbf1b4598, v168
	v_mul_f32_e32 v169, 0xbf1b4598, v169
	v_mul_f32_e32 v164, 0xbf1b4598, v164
	v_mul_f32_e32 v165, 0xbf1b4598, v165
	v_mul_f32_e32 v166, 0x3fb8aa3b, v166
	v_mul_f32_e32 v167, 0x3fb8aa3b, v167
	v_mul_f32_e32 v168, 0x3fb8aa3b, v168
	v_mul_f32_e32 v169, 0x3fb8aa3b, v169
	v_mul_f32_e32 v164, 0x3fb8aa3b, v164
	v_mul_f32_e32 v165, 0x3fb8aa3b, v165
	v_exp_f32_e32 v166, v166
	v_exp_f32_e32 v167, v167
	v_exp_f32_e32 v168, v168
	v_exp_f32_e32 v169, v169
	v_exp_f32_e32 v164, v164
	v_exp_f32_e32 v165, v165
	s_add_u32 s24, s18, s54
	v_sub_f32_e32 v162, 1.0, v162
	v_sub_f32_e32 v163, 1.0, v163
	s_addc_u32 s25, s19, s57
	v_cvt_pk_bf16_f32 v172, v162, v163
	v_mov_b64_e32 v[162:163], s[24:25]
	v_mad_i64_i32 v[174:175], s[24:25], v176, s3, v[162:163]
	v_sub_f32_e32 v166, 1.0, v166
	v_sub_f32_e32 v167, 1.0, v167
	v_sub_f32_e32 v168, 1.0, v168
	v_sub_f32_e32 v169, 1.0, v169
	v_sub_f32_e32 v164, 1.0, v164
	v_sub_f32_e32 v165, 1.0, v165
	v_cvt_pk_bf16_f32 v170, v166, v167
	v_cvt_pk_bf16_f32 v171, v168, v169
	v_cvt_pk_bf16_f32 v173, v164, v165

.LBB0_698:
	s_and_b64 vcc, exec, s[24:25]
	s_cbranch_vccz .LBB0_700
	s_nop 0
	v_add_f32_e32 v162, v158, v134
	v_mul_f32_e32 v162, 0xbfb8aa3b, v162
	v_add_f32_e32 v163, v159, v135
	v_exp_f32_e32 v162, v162
	v_mul_f32_e32 v163, 0xbfb8aa3b, v163
	v_exp_f32_e32 v163, v163
	v_add_f32_e32 v164, v161, v137
	v_add_f32_e32 v162, 1.0, v162
	v_rcp_f32_e32 v169, v162
	v_add_f32_e32 v162, 1.0, v163
	v_add_f32_e32 v163, v160, v136
	v_mul_f32_e32 v163, 0xbfb8aa3b, v163
	v_exp_f32_e32 v163, v163
	v_mul_f32_e32 v164, 0xbfb8aa3b, v164
	v_exp_f32_e32 v164, v164
	v_rcp_f32_e32 v170, v162
	v_add_f32_e32 v162, 1.0, v163
	v_add_f32_e32 v163, v154, v126
	v_rcp_f32_e32 v171, v162
	v_add_f32_e32 v162, 1.0, v164
	v_mul_f32_e32 v163, 0xbfb8aa3b, v163
	v_add_f32_e32 v164, v155, v127
	v_exp_f32_e32 v163, v163
	v_mul_f32_e32 v164, 0xbfb8aa3b, v164
	v_exp_f32_e32 v164, v164
	v_rcp_f32_e32 v172, v162
	v_add_f32_e32 v162, 1.0, v163
	v_add_f32_e32 v163, v156, v128
	v_rcp_f32_e32 v173, v162
	v_add_f32_e32 v162, 1.0, v164
	v_mul_f32_e32 v163, 0xbfb8aa3b, v163
	v_add_f32_e32 v164, v157, v129
	v_exp_f32_e32 v163, v163
	v_mul_f32_e32 v164, 0xbfb8aa3b, v164
	v_exp_f32_e32 v164, v164
	v_rcp_f32_e32 v174, v162
	v_add_f32_e32 v162, 1.0, v163
	v_rcp_f32_e32 v175, v162
	v_add_f32_e32 v162, 1.0, v164
	v_rcp_f32_e32 v176, v162
	v_lshlrev_b32_e32 v162, 16, v62
	v_and_b32_e32 v163, 0xffff0000, v62
	v_lshlrev_b32_e32 v164, 16, v63
	v_lshlrev_b32_e32 v166, 16, v64
	v_and_b32_e32 v167, 0xffff0000, v64
	s_add_u32 s24, s18, s56
	v_and_b32_e32 v165, 0xffff0000, v63
	v_mul_f32_e32 v162, v169, v162
	v_mul_f32_e32 v163, v170, v163
	v_mul_f32_e32 v164, v171, v164
	v_mul_f32_e32 v166, v173, v166
	v_mul_f32_e32 v167, v174, v167
	s_addc_u32 s25, s19, s77
	v_mul_f32_e32 v165, v172, v165
	v_cvt_pk_bf16_f32 v162, v162, v163
	v_cvt_pk_bf16_f32 v163, v164, v165
	v_cvt_pk_bf16_f32 v164, v166, v167
	v_mov_b64_e32 v[166:167], s[24:25]
	v_mad_i64_i32 v[166:167], s[24:25], v168, s3, v[166:167]
	v_lshlrev_b32_e32 v177, 16, v65
	v_and_b32_e32 v178, 0xffff0000, v65
	v_lshl_add_u64 v[166:167], v[198:199], 1, v[166:167]
	v_add_f32_e32 v169, -1.0, v169
	v_mul_f32_e32 v177, v175, v177
	v_mul_f32_e32 v178, v176, v178
	v_cvt_pk_bf16_f32 v165, v177, v178
	global_store_dwordx4 v[166:167], v[162:165], off
	v_fma_f32 v169, v142, v169, 1.0
	v_lshlrev_b32_e32 v166, 16, v56
	v_lshlrev_b32_e32 v162, 16, v54
	v_mul_f32_e32 v162, v169, v162
	v_add_f32_e32 v169, -1.0, v170
	v_and_b32_e32 v163, 0xffff0000, v54
	v_fma_f32 v169, v143, v169, 1.0
	v_mul_f32_e32 v163, v169, v163
	v_add_f32_e32 v169, -1.0, v171
	v_lshlrev_b32_e32 v164, 16, v55
	v_fma_f32 v169, v144, v169, 1.0
	v_mul_f32_e32 v164, v169, v164
	v_add_f32_e32 v169, -1.0, v172
	v_and_b32_e32 v165, 0xffff0000, v55
	v_fma_f32 v169, v145, v169, 1.0
	v_mul_f32_e32 v165, v169, v165
	v_add_f32_e32 v169, -1.0, v173
	v_fma_f32 v169, v138, v169, 1.0
	v_mul_f32_e32 v166, v169, v166
	v_add_f32_e32 v169, -1.0, v174
	v_and_b32_e32 v167, 0xffff0000, v56
	v_fma_f32 v169, v139, v169, 1.0
	s_add_u32 s24, s18, s76
	v_mul_f32_e32 v167, v169, v167
	s_addc_u32 s25, s19, s86
	v_add_f32_e32 v169, -1.0, v175
	v_add_f32_e32 v170, -1.0, v176
	v_cvt_pk_bf16_f32 v162, v162, v163
	v_cvt_pk_bf16_f32 v163, v164, v165
	v_cvt_pk_bf16_f32 v164, v166, v167
	v_mov_b64_e32 v[166:167], s[24:25]
	v_lshlrev_b32_e32 v177, 16, v57
	v_and_b32_e32 v178, 0xffff0000, v57
	v_fma_f32 v169, v140, v169, 1.0
	v_fma_f32 v170, v141, v170, 1.0
	v_mad_i64_i32 v[166:167], s[24:25], v168, s3, v[166:167]
	v_mul_f32_e32 v169, v169, v177
	v_mul_f32_e32 v170, v170, v178
	v_cvt_pk_bf16_f32 v165, v169, v170

.LBB0_701:
	s_andn2_b64 vcc, exec, s[24:25]
	s_cbranch_vccnz .LBB0_703
	s_nop 0
	v_add_f32_e32 v154, v154, v126
	v_add_f32_e32 v155, v155, v127
	v_mul_f32_e32 v154, 0xbfb8aa3b, v154
	v_mul_f32_e32 v155, 0xbfb8aa3b, v155
	v_exp_f32_e32 v154, v154
	v_exp_f32_e32 v155, v155
	v_add_f32_e32 v158, v158, v134
	v_add_f32_e32 v159, v159, v135
	v_add_f32_e32 v160, v160, v136
	v_add_f32_e32 v161, v161, v137
	v_add_f32_e32 v156, v156, v128
	v_add_f32_e32 v157, v157, v129
	v_mul_f32_e32 v158, 0xbfb8aa3b, v158
	v_mul_f32_e32 v159, 0xbfb8aa3b, v159
	v_mul_f32_e32 v160, 0xbfb8aa3b, v160
	v_mul_f32_e32 v161, 0xbfb8aa3b, v161
	v_mul_f32_e32 v156, 0xbfb8aa3b, v156
	v_mul_f32_e32 v157, 0xbfb8aa3b, v157
	v_exp_f32_e32 v158, v158
	v_exp_f32_e32 v159, v159
	v_exp_f32_e32 v160, v160
	v_exp_f32_e32 v161, v161
	v_exp_f32_e32 v156, v156
	v_exp_f32_e32 v157, v157
	v_add_f32_e32 v154, 1.0, v154
	v_add_f32_e32 v155, 1.0, v155
	v_rcp_f32_e32 v154, v154
	v_rcp_f32_e32 v155, v155
	v_add_f32_e32 v158, 1.0, v158
	v_add_f32_e32 v159, 1.0, v159
	v_add_f32_e32 v160, 1.0, v160
	v_add_f32_e32 v161, 1.0, v161
	v_add_f32_e32 v156, 1.0, v156
	v_add_f32_e32 v157, 1.0, v157
	v_rcp_f32_e32 v158, v158
	v_rcp_f32_e32 v159, v159
	v_rcp_f32_e32 v160, v160
	v_rcp_f32_e32 v161, v161
	v_rcp_f32_e32 v156, v156
	v_rcp_f32_e32 v157, v157
	v_mul_f32_e32 v154, 0xbf1b4598, v154
	v_mul_f32_e32 v155, 0xbf1b4598, v155
	v_mul_f32_e32 v154, 0x3fb8aa3b, v154
	v_mul_f32_e32 v155, 0x3fb8aa3b, v155
	v_exp_f32_e32 v154, v154
	v_exp_f32_e32 v155, v155
	v_mul_f32_e32 v158, 0xbf1b4598, v158
	v_mul_f32_e32 v159, 0xbf1b4598, v159
	v_mul_f32_e32 v160, 0xbf1b4598, v160
	v_mul_f32_e32 v161, 0xbf1b4598, v161
	v_mul_f32_e32 v156, 0xbf1b4598, v156
	v_mul_f32_e32 v157, 0xbf1b4598, v157
	v_mul_f32_e32 v158, 0x3fb8aa3b, v158
	v_mul_f32_e32 v159, 0x3fb8aa3b, v159
	v_mul_f32_e32 v160, 0x3fb8aa3b, v160
	v_mul_f32_e32 v161, 0x3fb8aa3b, v161
	v_mul_f32_e32 v156, 0x3fb8aa3b, v156
	v_mul_f32_e32 v157, 0x3fb8aa3b, v157
	v_exp_f32_e32 v158, v158
	v_exp_f32_e32 v159, v159
	v_exp_f32_e32 v160, v160
	v_exp_f32_e32 v161, v161
	v_exp_f32_e32 v156, v156
	v_exp_f32_e32 v157, v157
	s_add_u32 s24, s18, s54
	v_sub_f32_e32 v154, 1.0, v154
	v_sub_f32_e32 v155, 1.0, v155
	s_addc_u32 s25, s19, s57
	v_cvt_pk_bf16_f32 v164, v154, v155
	v_mov_b64_e32 v[154:155], s[24:25]
	v_mad_i64_i32 v[166:167], s[24:25], v168, s3, v[154:155]
	v_sub_f32_e32 v158, 1.0, v158
	v_sub_f32_e32 v159, 1.0, v159
	v_sub_f32_e32 v160, 1.0, v160
	v_sub_f32_e32 v161, 1.0, v161
	v_sub_f32_e32 v156, 1.0, v156
	v_sub_f32_e32 v157, 1.0, v157
	v_cvt_pk_bf16_f32 v162, v158, v159
	v_cvt_pk_bf16_f32 v163, v160, v161
	v_cvt_pk_bf16_f32 v165, v156, v157

.LBB0_710:
	s_and_b64 vcc, exec, s[24:25]
	s_cbranch_vccz .LBB0_712
	s_nop 0
	v_add_f32_e32 v154, v150, v134
	v_mul_f32_e32 v154, 0xbfb8aa3b, v154
	v_add_f32_e32 v155, v151, v135
	v_exp_f32_e32 v154, v154
	v_mul_f32_e32 v155, 0xbfb8aa3b, v155
	v_exp_f32_e32 v155, v155
	v_add_f32_e32 v156, v153, v137
	v_add_f32_e32 v154, 1.0, v154
	v_rcp_f32_e32 v161, v154
	v_add_f32_e32 v154, 1.0, v155
	v_add_f32_e32 v155, v152, v136
	v_mul_f32_e32 v155, 0xbfb8aa3b, v155
	v_exp_f32_e32 v155, v155
	v_mul_f32_e32 v156, 0xbfb8aa3b, v156
	v_exp_f32_e32 v156, v156
	v_rcp_f32_e32 v162, v154
	v_add_f32_e32 v154, 1.0, v155
	v_add_f32_e32 v155, v146, v126
	v_rcp_f32_e32 v163, v154
	v_add_f32_e32 v154, 1.0, v156
	v_mul_f32_e32 v155, 0xbfb8aa3b, v155
	v_add_f32_e32 v156, v147, v127
	v_exp_f32_e32 v155, v155
	v_mul_f32_e32 v156, 0xbfb8aa3b, v156
	v_exp_f32_e32 v156, v156
	v_rcp_f32_e32 v164, v154
	v_add_f32_e32 v154, 1.0, v155
	v_add_f32_e32 v155, v148, v128
	v_rcp_f32_e32 v165, v154
	v_add_f32_e32 v154, 1.0, v156
	v_mul_f32_e32 v155, 0xbfb8aa3b, v155
	v_add_f32_e32 v156, v149, v129
	v_exp_f32_e32 v155, v155
	v_mul_f32_e32 v156, 0xbfb8aa3b, v156
	v_exp_f32_e32 v156, v156
	v_rcp_f32_e32 v166, v154
	v_add_f32_e32 v154, 1.0, v155
	v_rcp_f32_e32 v167, v154
	v_add_f32_e32 v154, 1.0, v156
	v_rcp_f32_e32 v168, v154
	v_lshlrev_b32_e32 v154, 16, v46
	v_and_b32_e32 v155, 0xffff0000, v46
	v_lshlrev_b32_e32 v156, 16, v47
	v_lshlrev_b32_e32 v158, 16, v48
	v_and_b32_e32 v159, 0xffff0000, v48
	s_add_u32 s24, s18, s56
	v_and_b32_e32 v157, 0xffff0000, v47
	v_mul_f32_e32 v154, v161, v154
	v_mul_f32_e32 v155, v162, v155
	v_mul_f32_e32 v156, v163, v156
	v_mul_f32_e32 v158, v165, v158
	v_mul_f32_e32 v159, v166, v159
	s_addc_u32 s25, s19, s77
	v_mul_f32_e32 v157, v164, v157
	v_cvt_pk_bf16_f32 v154, v154, v155
	v_cvt_pk_bf16_f32 v155, v156, v157
	v_cvt_pk_bf16_f32 v156, v158, v159
	v_mov_b64_e32 v[158:159], s[24:25]
	v_mad_i64_i32 v[158:159], s[24:25], v160, s3, v[158:159]
	v_lshlrev_b32_e32 v169, 16, v49
	v_and_b32_e32 v170, 0xffff0000, v49
	v_lshl_add_u64 v[158:159], v[198:199], 1, v[158:159]
	v_add_f32_e32 v161, -1.0, v161
	v_mul_f32_e32 v169, v167, v169
	v_mul_f32_e32 v170, v168, v170
	v_cvt_pk_bf16_f32 v157, v169, v170
	global_store_dwordx4 v[158:159], v[154:157], off
	v_fma_f32 v161, v142, v161, 1.0
	v_lshlrev_b32_e32 v158, 16, v44
	v_lshlrev_b32_e32 v154, 16, v42
	v_mul_f32_e32 v154, v161, v154
	v_add_f32_e32 v161, -1.0, v162
	v_and_b32_e32 v155, 0xffff0000, v42
	v_fma_f32 v161, v143, v161, 1.0
	v_mul_f32_e32 v155, v161, v155
	v_add_f32_e32 v161, -1.0, v163
	v_lshlrev_b32_e32 v156, 16, v43
	v_fma_f32 v161, v144, v161, 1.0
	v_mul_f32_e32 v156, v161, v156
	v_add_f32_e32 v161, -1.0, v164
	v_and_b32_e32 v157, 0xffff0000, v43
	v_fma_f32 v161, v145, v161, 1.0
	v_mul_f32_e32 v157, v161, v157
	v_add_f32_e32 v161, -1.0, v165
	v_fma_f32 v161, v138, v161, 1.0
	v_mul_f32_e32 v158, v161, v158
	v_add_f32_e32 v161, -1.0, v166
	v_and_b32_e32 v159, 0xffff0000, v44
	v_fma_f32 v161, v139, v161, 1.0
	s_add_u32 s24, s18, s76
	v_mul_f32_e32 v159, v161, v159
	s_addc_u32 s25, s19, s86
	v_add_f32_e32 v161, -1.0, v167
	v_add_f32_e32 v162, -1.0, v168
	v_cvt_pk_bf16_f32 v154, v154, v155
	v_cvt_pk_bf16_f32 v155, v156, v157
	v_cvt_pk_bf16_f32 v156, v158, v159
	v_mov_b64_e32 v[158:159], s[24:25]
	v_lshlrev_b32_e32 v169, 16, v45
	v_and_b32_e32 v170, 0xffff0000, v45
	v_fma_f32 v161, v140, v161, 1.0
	v_fma_f32 v162, v141, v162, 1.0
	v_mad_i64_i32 v[158:159], s[24:25], v160, s3, v[158:159]
	v_mul_f32_e32 v161, v161, v169
	v_mul_f32_e32 v162, v162, v170
	v_cvt_pk_bf16_f32 v157, v161, v162

.LBB0_713:
	s_andn2_b64 vcc, exec, s[24:25]
	s_cbranch_vccnz .LBB0_715
	s_nop 0
	v_add_f32_e32 v146, v146, v126
	v_add_f32_e32 v147, v147, v127
	v_mul_f32_e32 v146, 0xbfb8aa3b, v146
	v_mul_f32_e32 v147, 0xbfb8aa3b, v147
	v_exp_f32_e32 v146, v146
	v_exp_f32_e32 v147, v147
	v_add_f32_e32 v150, v150, v134
	v_add_f32_e32 v151, v151, v135
	v_add_f32_e32 v152, v152, v136
	v_add_f32_e32 v153, v153, v137
	v_add_f32_e32 v148, v148, v128
	v_add_f32_e32 v149, v149, v129
	v_mul_f32_e32 v150, 0xbfb8aa3b, v150
	v_mul_f32_e32 v151, 0xbfb8aa3b, v151
	v_mul_f32_e32 v152, 0xbfb8aa3b, v152
	v_mul_f32_e32 v153, 0xbfb8aa3b, v153
	v_mul_f32_e32 v148, 0xbfb8aa3b, v148
	v_mul_f32_e32 v149, 0xbfb8aa3b, v149
	v_exp_f32_e32 v150, v150
	v_exp_f32_e32 v151, v151
	v_exp_f32_e32 v152, v152
	v_exp_f32_e32 v153, v153
	v_exp_f32_e32 v148, v148
	v_exp_f32_e32 v149, v149
	v_add_f32_e32 v146, 1.0, v146
	v_add_f32_e32 v147, 1.0, v147
	v_rcp_f32_e32 v146, v146
	v_rcp_f32_e32 v147, v147
	v_add_f32_e32 v150, 1.0, v150
	v_add_f32_e32 v151, 1.0, v151
	v_add_f32_e32 v152, 1.0, v152
	v_add_f32_e32 v153, 1.0, v153
	v_add_f32_e32 v148, 1.0, v148
	v_add_f32_e32 v149, 1.0, v149
	v_rcp_f32_e32 v150, v150
	v_rcp_f32_e32 v151, v151
	v_rcp_f32_e32 v152, v152
	v_rcp_f32_e32 v153, v153
	v_rcp_f32_e32 v148, v148
	v_rcp_f32_e32 v149, v149
	v_mul_f32_e32 v146, 0xbf1b4598, v146
	v_mul_f32_e32 v147, 0xbf1b4598, v147
	v_mul_f32_e32 v146, 0x3fb8aa3b, v146
	v_mul_f32_e32 v147, 0x3fb8aa3b, v147
	v_exp_f32_e32 v146, v146
	v_exp_f32_e32 v147, v147
	v_mul_f32_e32 v150, 0xbf1b4598, v150
	v_mul_f32_e32 v151, 0xbf1b4598, v151
	v_mul_f32_e32 v152, 0xbf1b4598, v152
	v_mul_f32_e32 v153, 0xbf1b4598, v153
	v_mul_f32_e32 v148, 0xbf1b4598, v148
	v_mul_f32_e32 v149, 0xbf1b4598, v149
	v_mul_f32_e32 v150, 0x3fb8aa3b, v150
	v_mul_f32_e32 v151, 0x3fb8aa3b, v151
	v_mul_f32_e32 v152, 0x3fb8aa3b, v152
	v_mul_f32_e32 v153, 0x3fb8aa3b, v153
	v_mul_f32_e32 v148, 0x3fb8aa3b, v148
	v_mul_f32_e32 v149, 0x3fb8aa3b, v149
	v_exp_f32_e32 v150, v150
	v_exp_f32_e32 v151, v151
	v_exp_f32_e32 v152, v152
	v_exp_f32_e32 v153, v153
	v_exp_f32_e32 v148, v148
	v_exp_f32_e32 v149, v149
	s_add_u32 s24, s18, s54
	v_sub_f32_e32 v146, 1.0, v146
	v_sub_f32_e32 v147, 1.0, v147
	s_addc_u32 s25, s19, s57
	v_cvt_pk_bf16_f32 v156, v146, v147
	v_mov_b64_e32 v[146:147], s[24:25]
	v_mad_i64_i32 v[158:159], s[24:25], v160, s3, v[146:147]
	v_sub_f32_e32 v150, 1.0, v150
	v_sub_f32_e32 v151, 1.0, v151
	v_sub_f32_e32 v152, 1.0, v152
	v_sub_f32_e32 v153, 1.0, v153
	v_sub_f32_e32 v148, 1.0, v148
	v_sub_f32_e32 v149, 1.0, v149
	v_cvt_pk_bf16_f32 v154, v150, v151
	v_cvt_pk_bf16_f32 v155, v152, v153
	v_cvt_pk_bf16_f32 v157, v148, v149
.LBB0_715:
	v_lshl_add_u64 v[146:147], v[198:199], 1, v[158:159]
	global_store_dwordx4 v[146:147], v[154:157], off
	s_andn2_b64 vcc, exec, s[28:29]
	v_add_u32_e32 v152, 0x80, v219
	s_cbranch_vccnz .LBB0_717
	s_nop 0
	v_mad_i64_i32 v[42:43], s[24:25], v152, s3, v[202:203]
	v_mad_i64_i32 v[44:45], s[24:25], v152, s3, v[200:201]
	global_load_dwordx4 v[90:93], v[42:43], off
	global_load_dwordx4 v[82:85], v[44:45], off
	v_add_u32_e32 v44, 0x90, v219
	v_mad_i64_i32 v[42:43], s[24:25], v44, s3, v[202:203]
	v_mad_i64_i32 v[44:45], s[24:25], v44, s3, v[200:201]
	global_load_dwordx4 v[74:77], v[42:43], off
	global_load_dwordx4 v[70:73], v[44:45], off
	v_add_u32_e32 v44, 0xa0, v219
	v_mad_i64_i32 v[42:43], s[24:25], v44, s3, v[202:203]
	v_mad_i64_i32 v[44:45], s[24:25], v44, s3, v[200:201]
	global_load_dwordx4 v[62:65], v[42:43], off
	global_load_dwordx4 v[54:57], v[44:45], off
	v_add_u32_e32 v44, 0xb0, v219
	v_mad_i64_i32 v[42:43], s[24:25], v44, s3, v[202:203]
	v_mad_i64_i32 v[44:45], s[24:25], v44, s3, v[200:201]
	global_load_dwordx4 v[46:49], v[42:43], off
	s_nop 0
	global_load_dwordx4 v[42:45], v[44:45], off

.LBB0_734:
	s_andn2_b64 vcc, exec, s[26:27]
	s_cbranch_vccnz .LBB0_736
	s_mul_i32 s26, s54, 0x180
	s_ashr_i32 s27, s26, 31
	s_lshl_b64 s[26:27], s[26:27], 2
	s_add_u32 s26, s30, s26
	s_addc_u32 s27, s31, s27
	v_ashrrev_i32_e32 v119, 31, v118
	s_nop 0
	v_lshl_add_u64 v[98:99], v[118:119], 2, s[26:27]
	global_load_dwordx4 v[102:105], v[98:99], off
	s_nop 0
	global_load_dwordx4 v[98:101], v[98:99], off offset:16
	v_mov_b32_e32 v109, 0
	v_mov_b32_e32 v108, v109
	v_mov_b32_e32 v107, v109
	v_mov_b32_e32 v106, v109
	v_mov_b32_e32 v113, v109
	v_mov_b32_e32 v112, v109
	v_mov_b32_e32 v111, v109
	v_mov_b32_e32 v110, v109

.LBB0_757:
	s_and_b64 vcc, exec, s[24:25]
	s_cbranch_vccz .LBB0_759
	v_add_f32_e32 v86, v78, v102
	v_mul_f32_e32 v86, 0xbfb8aa3b, v86
	v_add_f32_e32 v87, v79, v103
	v_exp_f32_e32 v86, v86
	v_mul_f32_e32 v87, 0xbfb8aa3b, v87
	v_exp_f32_e32 v87, v87
	v_add_f32_e32 v88, v81, v105
	v_add_f32_e32 v86, 1.0, v86
	v_rcp_f32_e32 v96, v86
	v_add_f32_e32 v86, 1.0, v87
	v_add_f32_e32 v87, v80, v104
	v_mul_f32_e32 v87, 0xbfb8aa3b, v87
	v_exp_f32_e32 v87, v87
	v_mul_f32_e32 v88, 0xbfb8aa3b, v88
	v_exp_f32_e32 v88, v88
	v_rcp_f32_e32 v97, v86
	v_add_f32_e32 v86, 1.0, v87
	v_add_f32_e32 v87, v66, v98
	v_rcp_f32_e32 v114, v86
	v_add_f32_e32 v86, 1.0, v88
	v_mul_f32_e32 v87, 0xbfb8aa3b, v87
	v_add_f32_e32 v88, v67, v99
	v_exp_f32_e32 v87, v87
	v_mul_f32_e32 v88, 0xbfb8aa3b, v88
	v_exp_f32_e32 v88, v88
	v_rcp_f32_e32 v115, v86
	v_add_f32_e32 v86, 1.0, v87
	v_add_f32_e32 v87, v68, v100
	v_rcp_f32_e32 v116, v86
	v_add_f32_e32 v86, 1.0, v88
	v_mul_f32_e32 v87, 0xbfb8aa3b, v87
	v_add_f32_e32 v88, v69, v101
	v_exp_f32_e32 v87, v87
	v_mul_f32_e32 v88, 0xbfb8aa3b, v88
	v_exp_f32_e32 v88, v88
	v_rcp_f32_e32 v117, v86
	v_add_f32_e32 v86, 1.0, v87
	v_rcp_f32_e32 v124, v86
	v_add_f32_e32 v86, 1.0, v88
	v_rcp_f32_e32 v125, v86
	s_nop 0
	v_lshlrev_b32_e32 v86, 16, v74
	v_and_b32_e32 v87, 0xffff0000, v74
	v_lshlrev_b32_e32 v88, 16, v75
	v_lshlrev_b32_e32 v94, 16, v76
	v_and_b32_e32 v95, 0xffff0000, v76
	s_add_u32 s24, s18, s57
	v_and_b32_e32 v89, 0xffff0000, v75
	v_mul_f32_e32 v86, v96, v86
	v_mul_f32_e32 v87, v97, v87
	v_mul_f32_e32 v88, v114, v88
	v_mul_f32_e32 v94, v116, v94
	v_mul_f32_e32 v95, v117, v95
	s_addc_u32 s25, s19, s56
	v_mul_f32_e32 v89, v115, v89
	v_cvt_pk_bf16_f32 v86, v86, v87
	v_cvt_pk_bf16_f32 v87, v88, v89
	v_cvt_pk_bf16_f32 v88, v94, v95
	v_mov_b64_e32 v[94:95], s[24:25]
	v_mad_i64_i32 v[94:95], s[24:25], v128, s3, v[94:95]
	v_lshlrev_b32_e32 v129, 16, v77
	v_and_b32_e32 v130, 0xffff0000, v77
	v_lshl_add_u64 v[94:95], v[118:119], 1, v[94:95]
	v_add_f32_e32 v96, -1.0, v96
	v_mul_f32_e32 v129, v124, v129
	v_mul_f32_e32 v130, v125, v130
	v_cvt_pk_bf16_f32 v89, v129, v130
	global_store_dwordx4 v[94:95], v[86:89], off
	v_fma_f32 v96, v110, v96, 1.0
	v_lshlrev_b32_e32 v94, 16, v72
	v_lshlrev_b32_e32 v86, 16, v70
	v_mul_f32_e32 v86, v96, v86
	v_add_f32_e32 v96, -1.0, v97
	v_and_b32_e32 v87, 0xffff0000, v70
	v_fma_f32 v96, v111, v96, 1.0
	v_mul_f32_e32 v87, v96, v87
	v_add_f32_e32 v96, -1.0, v114
	v_lshlrev_b32_e32 v88, 16, v71
	v_fma_f32 v96, v112, v96, 1.0
	v_mul_f32_e32 v88, v96, v88
	v_add_f32_e32 v96, -1.0, v115
	v_and_b32_e32 v89, 0xffff0000, v71
	v_fma_f32 v96, v113, v96, 1.0
	v_mul_f32_e32 v89, v96, v89
	v_add_f32_e32 v96, -1.0, v116
	v_fma_f32 v96, v106, v96, 1.0
	v_mul_f32_e32 v94, v96, v94
	v_add_f32_e32 v96, -1.0, v117
	v_and_b32_e32 v95, 0xffff0000, v72
	v_fma_f32 v96, v107, v96, 1.0
	s_add_u32 s24, s18, s86
	v_mul_f32_e32 v95, v96, v95
	s_addc_u32 s25, s19, s76
	v_add_f32_e32 v96, -1.0, v124
	v_add_f32_e32 v97, -1.0, v125
	v_cvt_pk_bf16_f32 v86, v86, v87
	v_cvt_pk_bf16_f32 v87, v88, v89
	v_cvt_pk_bf16_f32 v88, v94, v95
	v_mov_b64_e32 v[94:95], s[24:25]
	v_lshlrev_b32_e32 v129, 16, v73
	v_and_b32_e32 v130, 0xffff0000, v73
	v_fma_f32 v96, v108, v96, 1.0
	v_fma_f32 v97, v109, v97, 1.0
	v_mad_i64_i32 v[94:95], s[24:25], v128, s3, v[94:95]
	v_mul_f32_e32 v96, v96, v129
	v_mul_f32_e32 v97, v97, v130
	v_cvt_pk_bf16_f32 v89, v96, v97

.LBB0_769:
	s_and_b64 vcc, exec, s[24:25]
	s_cbranch_vccz .LBB0_771
	v_add_f32_e32 v66, v58, v102
	v_mul_f32_e32 v66, 0xbfb8aa3b, v66
	v_add_f32_e32 v67, v59, v103
	v_exp_f32_e32 v66, v66
	v_mul_f32_e32 v67, 0xbfb8aa3b, v67
	v_exp_f32_e32 v67, v67
	v_add_f32_e32 v68, v61, v105
	v_add_f32_e32 v66, 1.0, v66
	v_rcp_f32_e32 v80, v66
	v_add_f32_e32 v66, 1.0, v67
	v_add_f32_e32 v67, v60, v104
	v_mul_f32_e32 v67, 0xbfb8aa3b, v67
	v_exp_f32_e32 v67, v67
	v_mul_f32_e32 v68, 0xbfb8aa3b, v68
	v_exp_f32_e32 v68, v68
	v_rcp_f32_e32 v81, v66
	v_add_f32_e32 v66, 1.0, v67
	v_add_f32_e32 v67, v50, v98
	v_rcp_f32_e32 v86, v66
	v_add_f32_e32 v66, 1.0, v68
	v_mul_f32_e32 v67, 0xbfb8aa3b, v67
	v_add_f32_e32 v68, v51, v99
	v_exp_f32_e32 v67, v67
	v_mul_f32_e32 v68, 0xbfb8aa3b, v68
	v_exp_f32_e32 v68, v68
	v_rcp_f32_e32 v87, v66
	v_add_f32_e32 v66, 1.0, v67
	v_add_f32_e32 v67, v52, v100
	v_rcp_f32_e32 v88, v66
	v_add_f32_e32 v66, 1.0, v68
	v_mul_f32_e32 v67, 0xbfb8aa3b, v67
	v_add_f32_e32 v68, v53, v101
	v_exp_f32_e32 v67, v67
	v_mul_f32_e32 v68, 0xbfb8aa3b, v68
	v_exp_f32_e32 v68, v68
	v_rcp_f32_e32 v89, v66
	v_add_f32_e32 v66, 1.0, v67
	v_rcp_f32_e32 v94, v66
	v_add_f32_e32 v66, 1.0, v68
	v_rcp_f32_e32 v95, v66
	s_nop 0
	v_lshlrev_b32_e32 v66, 16, v62
	v_and_b32_e32 v67, 0xffff0000, v62
	v_lshlrev_b32_e32 v68, 16, v63
	v_lshlrev_b32_e32 v78, 16, v64
	v_and_b32_e32 v79, 0xffff0000, v64
	s_add_u32 s24, s18, s57
	v_and_b32_e32 v69, 0xffff0000, v63
	v_mul_f32_e32 v66, v80, v66
	v_mul_f32_e32 v67, v81, v67
	v_mul_f32_e32 v68, v86, v68
	v_mul_f32_e32 v78, v88, v78
	v_mul_f32_e32 v79, v89, v79
	s_addc_u32 s25, s19, s56
	v_mul_f32_e32 v69, v87, v69
	v_cvt_pk_bf16_f32 v66, v66, v67
	v_cvt_pk_bf16_f32 v67, v68, v69
	v_cvt_pk_bf16_f32 v68, v78, v79
	v_mov_b64_e32 v[78:79], s[24:25]
	v_mad_i64_i32 v[78:79], s[24:25], v127, s3, v[78:79]
	v_lshlrev_b32_e32 v96, 16, v65
	v_and_b32_e32 v97, 0xffff0000, v65
	v_lshl_add_u64 v[78:79], v[118:119], 1, v[78:79]
	v_add_f32_e32 v80, -1.0, v80
	v_mul_f32_e32 v96, v94, v96
	v_mul_f32_e32 v97, v95, v97
	v_cvt_pk_bf16_f32 v69, v96, v97
	global_store_dwordx4 v[78:79], v[66:69], off
	v_fma_f32 v80, v110, v80, 1.0
	v_lshlrev_b32_e32 v78, 16, v56
	v_lshlrev_b32_e32 v66, 16, v54
	v_mul_f32_e32 v66, v80, v66
	v_add_f32_e32 v80, -1.0, v81
	v_and_b32_e32 v67, 0xffff0000, v54
	v_fma_f32 v80, v111, v80, 1.0
	v_mul_f32_e32 v67, v80, v67
	v_add_f32_e32 v80, -1.0, v86
	v_lshlrev_b32_e32 v68, 16, v55
	v_fma_f32 v80, v112, v80, 1.0
	v_mul_f32_e32 v68, v80, v68
	v_add_f32_e32 v80, -1.0, v87
	v_and_b32_e32 v69, 0xffff0000, v55
	v_fma_f32 v80, v113, v80, 1.0
	v_mul_f32_e32 v69, v80, v69
	v_add_f32_e32 v80, -1.0, v88
	v_fma_f32 v80, v106, v80, 1.0
	v_mul_f32_e32 v78, v80, v78
	v_add_f32_e32 v80, -1.0, v89
	v_and_b32_e32 v79, 0xffff0000, v56
	v_fma_f32 v80, v107, v80, 1.0
	s_add_u32 s24, s18, s86
	v_mul_f32_e32 v79, v80, v79
	s_addc_u32 s25, s19, s76
	v_add_f32_e32 v80, -1.0, v94
	v_add_f32_e32 v81, -1.0, v95
	v_cvt_pk_bf16_f32 v66, v66, v67
	v_cvt_pk_bf16_f32 v67, v68, v69
	v_cvt_pk_bf16_f32 v68, v78, v79
	v_mov_b64_e32 v[78:79], s[24:25]
	v_lshlrev_b32_e32 v96, 16, v57
	v_and_b32_e32 v97, 0xffff0000, v57
	v_fma_f32 v80, v108, v80, 1.0
	v_fma_f32 v81, v109, v81, 1.0
	v_mad_i64_i32 v[78:79], s[24:25], v127, s3, v[78:79]
	v_mul_f32_e32 v80, v80, v96
	v_mul_f32_e32 v81, v81, v97
	v_cvt_pk_bf16_f32 v69, v80, v81

.LBB0_781:
	s_and_b64 vcc, exec, s[24:25]
	s_cbranch_vccz .LBB0_783
	v_add_f32_e32 v50, v38, v102
	v_mul_f32_e32 v50, 0xbfb8aa3b, v50
	v_add_f32_e32 v51, v39, v103
	v_exp_f32_e32 v50, v50
	v_mul_f32_e32 v51, 0xbfb8aa3b, v51
	v_exp_f32_e32 v51, v51
	v_add_f32_e32 v52, v41, v105
	v_add_f32_e32 v50, 1.0, v50
	v_rcp_f32_e32 v60, v50
	v_add_f32_e32 v50, 1.0, v51
	v_add_f32_e32 v51, v40, v104
	v_mul_f32_e32 v51, 0xbfb8aa3b, v51
	v_exp_f32_e32 v51, v51
	v_mul_f32_e32 v52, 0xbfb8aa3b, v52
	v_exp_f32_e32 v52, v52
	v_rcp_f32_e32 v61, v50
	v_add_f32_e32 v50, 1.0, v51
	v_add_f32_e32 v51, v34, v98
	v_rcp_f32_e32 v66, v50
	v_add_f32_e32 v50, 1.0, v52
	v_mul_f32_e32 v51, 0xbfb8aa3b, v51
	v_add_f32_e32 v52, v35, v99
	v_exp_f32_e32 v51, v51
	v_mul_f32_e32 v52, 0xbfb8aa3b, v52
	v_exp_f32_e32 v52, v52
	v_rcp_f32_e32 v67, v50
	v_add_f32_e32 v50, 1.0, v51
	v_add_f32_e32 v51, v36, v100
	v_rcp_f32_e32 v68, v50
	v_add_f32_e32 v50, 1.0, v52
	v_mul_f32_e32 v51, 0xbfb8aa3b, v51
	v_add_f32_e32 v52, v37, v101
	v_exp_f32_e32 v51, v51
	v_mul_f32_e32 v52, 0xbfb8aa3b, v52
	v_exp_f32_e32 v52, v52
	v_rcp_f32_e32 v69, v50
	v_add_f32_e32 v50, 1.0, v51
	v_rcp_f32_e32 v78, v50
	v_add_f32_e32 v50, 1.0, v52
	v_rcp_f32_e32 v79, v50
	s_nop 0
	v_lshlrev_b32_e32 v50, 16, v46
	v_and_b32_e32 v51, 0xffff0000, v46
	v_lshlrev_b32_e32 v52, 16, v47
	v_lshlrev_b32_e32 v58, 16, v48
	v_and_b32_e32 v59, 0xffff0000, v48
	s_add_u32 s24, s18, s57
	v_and_b32_e32 v53, 0xffff0000, v47
	v_mul_f32_e32 v50, v60, v50
	v_mul_f32_e32 v51, v61, v51
	v_mul_f32_e32 v52, v66, v52
	v_mul_f32_e32 v58, v68, v58
	v_mul_f32_e32 v59, v69, v59
	s_addc_u32 s25, s19, s56
	v_mul_f32_e32 v53, v67, v53
	v_cvt_pk_bf16_f32 v50, v50, v51
	v_cvt_pk_bf16_f32 v51, v52, v53
	v_cvt_pk_bf16_f32 v52, v58, v59
	v_mov_b64_e32 v[58:59], s[24:25]
	v_mad_i64_i32 v[58:59], s[24:25], v126, s3, v[58:59]
	v_lshlrev_b32_e32 v80, 16, v49
	v_and_b32_e32 v81, 0xffff0000, v49
	v_lshl_add_u64 v[58:59], v[118:119], 1, v[58:59]
	v_add_f32_e32 v60, -1.0, v60
	v_mul_f32_e32 v80, v78, v80
	v_mul_f32_e32 v81, v79, v81
	v_cvt_pk_bf16_f32 v53, v80, v81
	global_store_dwordx4 v[58:59], v[50:53], off
	v_fma_f32 v60, v110, v60, 1.0
	v_lshlrev_b32_e32 v58, 16, v44
	v_lshlrev_b32_e32 v50, 16, v42
	v_mul_f32_e32 v50, v60, v50
	v_add_f32_e32 v60, -1.0, v61
	v_and_b32_e32 v51, 0xffff0000, v42
	v_fma_f32 v60, v111, v60, 1.0
	v_mul_f32_e32 v51, v60, v51
	v_add_f32_e32 v60, -1.0, v66
	v_lshlrev_b32_e32 v52, 16, v43
	v_fma_f32 v60, v112, v60, 1.0
	v_mul_f32_e32 v52, v60, v52
	v_add_f32_e32 v60, -1.0, v67
	v_and_b32_e32 v53, 0xffff0000, v43
	v_fma_f32 v60, v113, v60, 1.0
	v_mul_f32_e32 v53, v60, v53
	v_add_f32_e32 v60, -1.0, v68
	v_fma_f32 v60, v106, v60, 1.0
	v_mul_f32_e32 v58, v60, v58
	v_add_f32_e32 v60, -1.0, v69
	v_and_b32_e32 v59, 0xffff0000, v44
	v_fma_f32 v60, v107, v60, 1.0
	s_add_u32 s24, s18, s86
	v_mul_f32_e32 v59, v60, v59
	s_addc_u32 s25, s19, s76
	v_add_f32_e32 v60, -1.0, v78
	v_add_f32_e32 v61, -1.0, v79
	v_cvt_pk_bf16_f32 v50, v50, v51
	v_cvt_pk_bf16_f32 v51, v52, v53
	v_cvt_pk_bf16_f32 v52, v58, v59
	v_mov_b64_e32 v[58:59], s[24:25]
	v_lshlrev_b32_e32 v80, 16, v45
	v_and_b32_e32 v81, 0xffff0000, v45
	v_fma_f32 v60, v108, v60, 1.0
	v_fma_f32 v61, v109, v61, 1.0
	v_mad_i64_i32 v[58:59], s[24:25], v126, s3, v[58:59]
	v_mul_f32_e32 v60, v60, v80
	v_mul_f32_e32 v61, v61, v81
	v_cvt_pk_bf16_f32 v53, v60, v61

.LBB0_799:
	s_nop 0
	v_add_f32_e32 v122, v122, v126
	v_add_f32_e32 v123, v123, v127
	v_mul_f32_e32 v122, 0xbfb8aa3b, v122
	v_mul_f32_e32 v123, 0xbfb8aa3b, v123
	v_exp_f32_e32 v122, v122
	v_exp_f32_e32 v123, v123
	v_add_f32_e32 v130, v130, v134
	v_add_f32_e32 v131, v131, v135
	v_add_f32_e32 v132, v132, v136
	v_add_f32_e32 v133, v133, v137
	v_add_f32_e32 v124, v124, v128
	v_add_f32_e32 v125, v125, v129
	v_mul_f32_e32 v130, 0xbfb8aa3b, v130
	v_mul_f32_e32 v131, 0xbfb8aa3b, v131
	v_mul_f32_e32 v132, 0xbfb8aa3b, v132
	v_mul_f32_e32 v133, 0xbfb8aa3b, v133
	v_mul_f32_e32 v124, 0xbfb8aa3b, v124
	v_mul_f32_e32 v125, 0xbfb8aa3b, v125
	v_exp_f32_e32 v130, v130
	v_exp_f32_e32 v131, v131
	v_exp_f32_e32 v132, v132
	v_exp_f32_e32 v133, v133
	v_exp_f32_e32 v124, v124
	v_exp_f32_e32 v125, v125
	v_add_f32_e32 v122, 1.0, v122
	v_add_f32_e32 v123, 1.0, v123
	v_rcp_f32_e32 v122, v122
	v_rcp_f32_e32 v123, v123
	v_add_f32_e32 v130, 1.0, v130
	v_add_f32_e32 v131, 1.0, v131
	v_add_f32_e32 v132, 1.0, v132
	v_add_f32_e32 v133, 1.0, v133
	v_add_f32_e32 v124, 1.0, v124
	v_add_f32_e32 v125, 1.0, v125
	v_rcp_f32_e32 v130, v130
	v_rcp_f32_e32 v131, v131
	v_rcp_f32_e32 v132, v132
	v_rcp_f32_e32 v133, v133
	v_rcp_f32_e32 v124, v124
	v_rcp_f32_e32 v125, v125
	v_mul_f32_e32 v122, 0xbf1b4598, v122
	v_mul_f32_e32 v123, 0xbf1b4598, v123
	v_mul_f32_e32 v122, 0x3fb8aa3b, v122
	v_mul_f32_e32 v123, 0x3fb8aa3b, v123
	v_exp_f32_e32 v122, v122
	v_exp_f32_e32 v123, v123
	v_mul_f32_e32 v130, 0xbf1b4598, v130
	v_mul_f32_e32 v131, 0xbf1b4598, v131
	v_mul_f32_e32 v132, 0xbf1b4598, v132
	v_mul_f32_e32 v133, 0xbf1b4598, v133
	v_mul_f32_e32 v124, 0xbf1b4598, v124
	v_mul_f32_e32 v125, 0xbf1b4598, v125
	v_mul_f32_e32 v130, 0x3fb8aa3b, v130
	v_mul_f32_e32 v131, 0x3fb8aa3b, v131
	v_mul_f32_e32 v132, 0x3fb8aa3b, v132
	v_mul_f32_e32 v133, 0x3fb8aa3b, v133
	v_mul_f32_e32 v124, 0x3fb8aa3b, v124
	v_mul_f32_e32 v125, 0x3fb8aa3b, v125
	v_exp_f32_e32 v130, v130
	v_exp_f32_e32 v131, v131
	v_exp_f32_e32 v132, v132
	v_exp_f32_e32 v133, v133
	v_exp_f32_e32 v124, v124
	v_exp_f32_e32 v125, v125
	s_add_u32 s24, s18, s54
	v_sub_f32_e32 v122, 1.0, v122
	v_sub_f32_e32 v123, 1.0, v123
	s_addc_u32 s25, s19, s57
	v_cvt_pk_bf16_f32 v148, v122, v123
	v_mov_b64_e32 v[122:123], s[24:25]
	v_mad_i64_i32 v[150:151], s[24:25], v152, s3, v[122:123]
	v_sub_f32_e32 v130, 1.0, v130
	v_sub_f32_e32 v131, 1.0, v131
	v_sub_f32_e32 v132, 1.0, v132
	v_sub_f32_e32 v133, 1.0, v133
	v_sub_f32_e32 v124, 1.0, v124
	v_sub_f32_e32 v125, 1.0, v125
	v_cvt_pk_bf16_f32 v146, v130, v131
	v_cvt_pk_bf16_f32 v147, v132, v133
	v_cvt_pk_bf16_f32 v149, v124, v125

.LBB0_807:
	s_and_b64 vcc, exec, s[24:25]
	s_cbranch_vccz .LBB0_809
	s_nop 0
	v_add_f32_e32 v122, v118, v134
	v_mul_f32_e32 v122, 0xbfb8aa3b, v122
	v_add_f32_e32 v123, v119, v135
	v_exp_f32_e32 v122, v122
	v_mul_f32_e32 v123, 0xbfb8aa3b, v123
	v_exp_f32_e32 v123, v123
	v_add_f32_e32 v124, v121, v137
	v_add_f32_e32 v122, 1.0, v122
	v_rcp_f32_e32 v133, v122
	v_add_f32_e32 v122, 1.0, v123
	v_add_f32_e32 v123, v120, v136
	v_mul_f32_e32 v123, 0xbfb8aa3b, v123
	v_exp_f32_e32 v123, v123
	v_mul_f32_e32 v124, 0xbfb8aa3b, v124
	v_exp_f32_e32 v124, v124
	v_rcp_f32_e32 v146, v122
	v_add_f32_e32 v122, 1.0, v123
	v_add_f32_e32 v123, v114, v126
	v_rcp_f32_e32 v147, v122
	v_add_f32_e32 v122, 1.0, v124
	v_mul_f32_e32 v123, 0xbfb8aa3b, v123
	v_add_f32_e32 v124, v115, v127
	v_exp_f32_e32 v123, v123
	v_mul_f32_e32 v124, 0xbfb8aa3b, v124
	v_exp_f32_e32 v124, v124
	v_rcp_f32_e32 v148, v122
	v_add_f32_e32 v122, 1.0, v123
	v_add_f32_e32 v123, v116, v128
	v_rcp_f32_e32 v149, v122
	v_add_f32_e32 v122, 1.0, v124
	v_mul_f32_e32 v123, 0xbfb8aa3b, v123
	v_add_f32_e32 v124, v117, v129
	v_exp_f32_e32 v123, v123
	v_mul_f32_e32 v124, 0xbfb8aa3b, v124
	v_exp_f32_e32 v124, v124
	v_rcp_f32_e32 v150, v122
	v_add_f32_e32 v122, 1.0, v123
	v_rcp_f32_e32 v151, v122
	v_add_f32_e32 v122, 1.0, v124
	v_rcp_f32_e32 v152, v122
	v_lshlrev_b32_e32 v122, 16, v74
	v_and_b32_e32 v123, 0xffff0000, v74
	v_lshlrev_b32_e32 v124, 16, v75
	v_lshlrev_b32_e32 v130, 16, v76
	v_and_b32_e32 v131, 0xffff0000, v76
	s_add_u32 s24, s18, s56
	v_and_b32_e32 v125, 0xffff0000, v75
	v_mul_f32_e32 v122, v133, v122
	v_mul_f32_e32 v123, v146, v123
	v_mul_f32_e32 v124, v147, v124
	v_mul_f32_e32 v130, v149, v130
	v_mul_f32_e32 v131, v150, v131
	s_addc_u32 s25, s19, s77
	v_mul_f32_e32 v125, v148, v125
	v_cvt_pk_bf16_f32 v122, v122, v123
	v_cvt_pk_bf16_f32 v123, v124, v125
	v_cvt_pk_bf16_f32 v124, v130, v131
	v_mov_b64_e32 v[130:131], s[24:25]
	v_mad_i64_i32 v[130:131], s[24:25], v132, s3, v[130:131]
	v_lshlrev_b32_e32 v153, 16, v77
	v_and_b32_e32 v154, 0xffff0000, v77
	v_lshl_add_u64 v[130:131], v[198:199], 1, v[130:131]
	v_add_f32_e32 v133, -1.0, v133
	v_mul_f32_e32 v153, v151, v153
	v_mul_f32_e32 v154, v152, v154
	v_cvt_pk_bf16_f32 v125, v153, v154
	global_store_dwordx4 v[130:131], v[122:125], off
	v_fma_f32 v133, v142, v133, 1.0
	v_lshlrev_b32_e32 v130, 16, v72
	v_lshlrev_b32_e32 v122, 16, v70
	v_mul_f32_e32 v122, v133, v122
	v_add_f32_e32 v133, -1.0, v146
	v_and_b32_e32 v123, 0xffff0000, v70
	v_fma_f32 v133, v143, v133, 1.0
	v_mul_f32_e32 v123, v133, v123
	v_add_f32_e32 v133, -1.0, v147
	v_lshlrev_b32_e32 v124, 16, v71
	v_fma_f32 v133, v144, v133, 1.0
	v_mul_f32_e32 v124, v133, v124
	v_add_f32_e32 v133, -1.0, v148
	v_and_b32_e32 v125, 0xffff0000, v71
	v_fma_f32 v133, v145, v133, 1.0
	v_mul_f32_e32 v125, v133, v125
	v_add_f32_e32 v133, -1.0, v149
	v_fma_f32 v133, v138, v133, 1.0
	v_mul_f32_e32 v130, v133, v130
	v_add_f32_e32 v133, -1.0, v150
	v_and_b32_e32 v131, 0xffff0000, v72
	v_fma_f32 v133, v139, v133, 1.0
	s_add_u32 s24, s18, s76
	v_mul_f32_e32 v131, v133, v131
	s_addc_u32 s25, s19, s86
	v_add_f32_e32 v133, -1.0, v151
	v_add_f32_e32 v146, -1.0, v152
	v_cvt_pk_bf16_f32 v122, v122, v123
	v_cvt_pk_bf16_f32 v123, v124, v125
	v_cvt_pk_bf16_f32 v124, v130, v131
	v_mov_b64_e32 v[130:131], s[24:25]
	v_lshlrev_b32_e32 v153, 16, v73
	v_and_b32_e32 v154, 0xffff0000, v73
	v_fma_f32 v133, v140, v133, 1.0
	v_fma_f32 v146, v141, v146, 1.0
	v_mad_i64_i32 v[130:131], s[24:25], v132, s3, v[130:131]
	v_mul_f32_e32 v133, v133, v153
	v_mul_f32_e32 v146, v146, v154
	v_cvt_pk_bf16_f32 v125, v133, v146

.LBB0_810:
	s_andn2_b64 vcc, exec, s[24:25]
	s_cbranch_vccnz .LBB0_812
	s_nop 0
	v_add_f32_e32 v114, v114, v126
	v_add_f32_e32 v115, v115, v127
	v_mul_f32_e32 v114, 0xbfb8aa3b, v114
	v_mul_f32_e32 v115, 0xbfb8aa3b, v115
	v_exp_f32_e32 v114, v114
	v_exp_f32_e32 v115, v115
	v_add_f32_e32 v118, v118, v134
	v_add_f32_e32 v119, v119, v135
	v_add_f32_e32 v120, v120, v136
	v_add_f32_e32 v121, v121, v137
	v_add_f32_e32 v116, v116, v128
	v_add_f32_e32 v117, v117, v129
	v_mul_f32_e32 v118, 0xbfb8aa3b, v118
	v_mul_f32_e32 v119, 0xbfb8aa3b, v119
	v_mul_f32_e32 v120, 0xbfb8aa3b, v120
	v_mul_f32_e32 v121, 0xbfb8aa3b, v121
	v_mul_f32_e32 v116, 0xbfb8aa3b, v116
	v_mul_f32_e32 v117, 0xbfb8aa3b, v117
	v_exp_f32_e32 v118, v118
	v_exp_f32_e32 v119, v119
	v_exp_f32_e32 v120, v120
	v_exp_f32_e32 v121, v121
	v_exp_f32_e32 v116, v116
	v_exp_f32_e32 v117, v117
	v_add_f32_e32 v114, 1.0, v114
	v_add_f32_e32 v115, 1.0, v115
	v_rcp_f32_e32 v114, v114
	v_rcp_f32_e32 v115, v115
	v_add_f32_e32 v118, 1.0, v118
	v_add_f32_e32 v119, 1.0, v119
	v_add_f32_e32 v120, 1.0, v120
	v_add_f32_e32 v121, 1.0, v121
	v_add_f32_e32 v116, 1.0, v116
	v_add_f32_e32 v117, 1.0, v117
	v_rcp_f32_e32 v118, v118
	v_rcp_f32_e32 v119, v119
	v_rcp_f32_e32 v120, v120
	v_rcp_f32_e32 v121, v121
	v_rcp_f32_e32 v116, v116
	v_rcp_f32_e32 v117, v117
	v_mul_f32_e32 v114, 0xbf1b4598, v114
	v_mul_f32_e32 v115, 0xbf1b4598, v115
	v_mul_f32_e32 v114, 0x3fb8aa3b, v114
	v_mul_f32_e32 v115, 0x3fb8aa3b, v115
	v_exp_f32_e32 v114, v114
	v_exp_f32_e32 v115, v115
	v_mul_f32_e32 v118, 0xbf1b4598, v118
	v_mul_f32_e32 v119, 0xbf1b4598, v119
	v_mul_f32_e32 v120, 0xbf1b4598, v120
	v_mul_f32_e32 v121, 0xbf1b4598, v121
	v_mul_f32_e32 v116, 0xbf1b4598, v116
	v_mul_f32_e32 v117, 0xbf1b4598, v117
	v_mul_f32_e32 v118, 0x3fb8aa3b, v118
	v_mul_f32_e32 v119, 0x3fb8aa3b, v119
	v_mul_f32_e32 v120, 0x3fb8aa3b, v120
	v_mul_f32_e32 v121, 0x3fb8aa3b, v121
	v_mul_f32_e32 v116, 0x3fb8aa3b, v116
	v_mul_f32_e32 v117, 0x3fb8aa3b, v117
	v_exp_f32_e32 v118, v118
	v_exp_f32_e32 v119, v119
	v_exp_f32_e32 v120, v120
	v_exp_f32_e32 v121, v121
	v_exp_f32_e32 v116, v116
	v_exp_f32_e32 v117, v117
	s_add_u32 s24, s18, s54
	v_sub_f32_e32 v114, 1.0, v114
	v_sub_f32_e32 v115, 1.0, v115
	s_addc_u32 s25, s19, s57
	v_cvt_pk_bf16_f32 v124, v114, v115
	v_mov_b64_e32 v[114:115], s[24:25]
	v_mad_i64_i32 v[130:131], s[24:25], v132, s3, v[114:115]
	v_sub_f32_e32 v118, 1.0, v118
	v_sub_f32_e32 v119, 1.0, v119
	v_sub_f32_e32 v120, 1.0, v120
	v_sub_f32_e32 v121, 1.0, v121
	v_sub_f32_e32 v116, 1.0, v116
	v_sub_f32_e32 v117, 1.0, v117
	v_cvt_pk_bf16_f32 v122, v118, v119
	v_cvt_pk_bf16_f32 v123, v120, v121
	v_cvt_pk_bf16_f32 v125, v116, v117

.LBB0_819:
	s_and_b64 vcc, exec, s[24:25]
	s_cbranch_vccz .LBB0_821
	s_nop 0
	v_add_f32_e32 v114, v110, v134
	v_mul_f32_e32 v114, 0xbfb8aa3b, v114
	v_add_f32_e32 v115, v111, v135
	v_exp_f32_e32 v114, v114
	v_mul_f32_e32 v115, 0xbfb8aa3b, v115
	v_exp_f32_e32 v115, v115
	v_add_f32_e32 v116, v113, v137
	v_add_f32_e32 v114, 1.0, v114
	v_rcp_f32_e32 v121, v114
	v_add_f32_e32 v114, 1.0, v115
	v_add_f32_e32 v115, v112, v136
	v_mul_f32_e32 v115, 0xbfb8aa3b, v115
	v_exp_f32_e32 v115, v115
	v_mul_f32_e32 v116, 0xbfb8aa3b, v116
	v_exp_f32_e32 v116, v116
	v_rcp_f32_e32 v122, v114
	v_add_f32_e32 v114, 1.0, v115
	v_add_f32_e32 v115, v106, v126
	v_rcp_f32_e32 v123, v114
	v_add_f32_e32 v114, 1.0, v116
	v_mul_f32_e32 v115, 0xbfb8aa3b, v115
	v_add_f32_e32 v116, v107, v127
	v_exp_f32_e32 v115, v115
	v_mul_f32_e32 v116, 0xbfb8aa3b, v116
	v_exp_f32_e32 v116, v116
	v_rcp_f32_e32 v124, v114
	v_add_f32_e32 v114, 1.0, v115
	v_add_f32_e32 v115, v108, v128
	v_rcp_f32_e32 v125, v114
	v_add_f32_e32 v114, 1.0, v116
	v_mul_f32_e32 v115, 0xbfb8aa3b, v115
	v_add_f32_e32 v116, v109, v129
	v_exp_f32_e32 v115, v115
	v_mul_f32_e32 v116, 0xbfb8aa3b, v116
	v_exp_f32_e32 v116, v116
	v_rcp_f32_e32 v130, v114
	v_add_f32_e32 v114, 1.0, v115
	v_rcp_f32_e32 v131, v114
	v_add_f32_e32 v114, 1.0, v116
	v_rcp_f32_e32 v132, v114
	v_lshlrev_b32_e32 v114, 16, v62
	v_and_b32_e32 v115, 0xffff0000, v62
	v_lshlrev_b32_e32 v116, 16, v63
	v_lshlrev_b32_e32 v118, 16, v64
	v_and_b32_e32 v119, 0xffff0000, v64
	s_add_u32 s24, s18, s56
	v_and_b32_e32 v117, 0xffff0000, v63
	v_mul_f32_e32 v114, v121, v114
	v_mul_f32_e32 v115, v122, v115
	v_mul_f32_e32 v116, v123, v116
	v_mul_f32_e32 v118, v125, v118
	v_mul_f32_e32 v119, v130, v119
	s_addc_u32 s25, s19, s77
	v_mul_f32_e32 v117, v124, v117
	v_cvt_pk_bf16_f32 v114, v114, v115
	v_cvt_pk_bf16_f32 v115, v116, v117
	v_cvt_pk_bf16_f32 v116, v118, v119
	v_mov_b64_e32 v[118:119], s[24:25]
	v_mad_i64_i32 v[118:119], s[24:25], v120, s3, v[118:119]
	v_lshlrev_b32_e32 v133, 16, v65
	v_and_b32_e32 v146, 0xffff0000, v65
	v_lshl_add_u64 v[118:119], v[198:199], 1, v[118:119]
	v_add_f32_e32 v121, -1.0, v121
	v_mul_f32_e32 v133, v131, v133
	v_mul_f32_e32 v146, v132, v146
	v_cvt_pk_bf16_f32 v117, v133, v146
	global_store_dwordx4 v[118:119], v[114:117], off
	v_fma_f32 v121, v142, v121, 1.0
	v_lshlrev_b32_e32 v118, 16, v56
	v_lshlrev_b32_e32 v114, 16, v54
	v_mul_f32_e32 v114, v121, v114
	v_add_f32_e32 v121, -1.0, v122
	v_and_b32_e32 v115, 0xffff0000, v54
	v_fma_f32 v121, v143, v121, 1.0
	v_mul_f32_e32 v115, v121, v115
	v_add_f32_e32 v121, -1.0, v123
	v_lshlrev_b32_e32 v116, 16, v55
	v_fma_f32 v121, v144, v121, 1.0
	v_mul_f32_e32 v116, v121, v116
	v_add_f32_e32 v121, -1.0, v124
	v_and_b32_e32 v117, 0xffff0000, v55
	v_fma_f32 v121, v145, v121, 1.0
	v_mul_f32_e32 v117, v121, v117
	v_add_f32_e32 v121, -1.0, v125
	v_fma_f32 v121, v138, v121, 1.0
	v_mul_f32_e32 v118, v121, v118
	v_add_f32_e32 v121, -1.0, v130
	v_and_b32_e32 v119, 0xffff0000, v56
	v_fma_f32 v121, v139, v121, 1.0
	s_add_u32 s24, s18, s76
	v_mul_f32_e32 v119, v121, v119
	s_addc_u32 s25, s19, s86
	v_add_f32_e32 v121, -1.0, v131
	v_add_f32_e32 v122, -1.0, v132
	v_cvt_pk_bf16_f32 v114, v114, v115
	v_cvt_pk_bf16_f32 v115, v116, v117
	v_cvt_pk_bf16_f32 v116, v118, v119
	v_mov_b64_e32 v[118:119], s[24:25]
	v_lshlrev_b32_e32 v133, 16, v57
	v_and_b32_e32 v146, 0xffff0000, v57
	v_fma_f32 v121, v140, v121, 1.0
	v_fma_f32 v122, v141, v122, 1.0
	v_mad_i64_i32 v[118:119], s[24:25], v120, s3, v[118:119]
	v_mul_f32_e32 v121, v121, v133
	v_mul_f32_e32 v122, v122, v146
	v_cvt_pk_bf16_f32 v117, v121, v122

.LBB0_822:
	s_andn2_b64 vcc, exec, s[24:25]
	s_cbranch_vccnz .LBB0_824
	s_nop 0
	v_add_f32_e32 v106, v106, v126
	v_add_f32_e32 v107, v107, v127
	v_mul_f32_e32 v106, 0xbfb8aa3b, v106
	v_mul_f32_e32 v107, 0xbfb8aa3b, v107
	v_exp_f32_e32 v106, v106
	v_exp_f32_e32 v107, v107
	v_add_f32_e32 v110, v110, v134
	v_add_f32_e32 v111, v111, v135
	v_add_f32_e32 v112, v112, v136
	v_add_f32_e32 v113, v113, v137
	v_add_f32_e32 v108, v108, v128
	v_add_f32_e32 v109, v109, v129
	v_mul_f32_e32 v110, 0xbfb8aa3b, v110
	v_mul_f32_e32 v111, 0xbfb8aa3b, v111
	v_mul_f32_e32 v112, 0xbfb8aa3b, v112
	v_mul_f32_e32 v113, 0xbfb8aa3b, v113
	v_mul_f32_e32 v108, 0xbfb8aa3b, v108
	v_mul_f32_e32 v109, 0xbfb8aa3b, v109
	v_exp_f32_e32 v110, v110
	v_exp_f32_e32 v111, v111
	v_exp_f32_e32 v112, v112
	v_exp_f32_e32 v113, v113
	v_exp_f32_e32 v108, v108
	v_exp_f32_e32 v109, v109
	v_add_f32_e32 v106, 1.0, v106
	v_add_f32_e32 v107, 1.0, v107
	v_rcp_f32_e32 v106, v106
	v_rcp_f32_e32 v107, v107
	v_add_f32_e32 v110, 1.0, v110
	v_add_f32_e32 v111, 1.0, v111
	v_add_f32_e32 v112, 1.0, v112
	v_add_f32_e32 v113, 1.0, v113
	v_add_f32_e32 v108, 1.0, v108
	v_add_f32_e32 v109, 1.0, v109
	v_rcp_f32_e32 v110, v110
	v_rcp_f32_e32 v111, v111
	v_rcp_f32_e32 v112, v112
	v_rcp_f32_e32 v113, v113
	v_rcp_f32_e32 v108, v108
	v_rcp_f32_e32 v109, v109
	v_mul_f32_e32 v106, 0xbf1b4598, v106
	v_mul_f32_e32 v107, 0xbf1b4598, v107
	v_mul_f32_e32 v106, 0x3fb8aa3b, v106
	v_mul_f32_e32 v107, 0x3fb8aa3b, v107
	v_exp_f32_e32 v106, v106
	v_exp_f32_e32 v107, v107
	v_mul_f32_e32 v110, 0xbf1b4598, v110
	v_mul_f32_e32 v111, 0xbf1b4598, v111
	v_mul_f32_e32 v112, 0xbf1b4598, v112
	v_mul_f32_e32 v113, 0xbf1b4598, v113
	v_mul_f32_e32 v108, 0xbf1b4598, v108
	v_mul_f32_e32 v109, 0xbf1b4598, v109
	v_mul_f32_e32 v110, 0x3fb8aa3b, v110
	v_mul_f32_e32 v111, 0x3fb8aa3b, v111
	v_mul_f32_e32 v112, 0x3fb8aa3b, v112
	v_mul_f32_e32 v113, 0x3fb8aa3b, v113
	v_mul_f32_e32 v108, 0x3fb8aa3b, v108
	v_mul_f32_e32 v109, 0x3fb8aa3b, v109
	v_exp_f32_e32 v110, v110
	v_exp_f32_e32 v111, v111
	v_exp_f32_e32 v112, v112
	v_exp_f32_e32 v113, v113
	v_exp_f32_e32 v108, v108
	v_exp_f32_e32 v109, v109
	s_add_u32 s24, s18, s54
	v_sub_f32_e32 v106, 1.0, v106
	v_sub_f32_e32 v107, 1.0, v107
	s_addc_u32 s25, s19, s57
	v_cvt_pk_bf16_f32 v116, v106, v107
	v_mov_b64_e32 v[106:107], s[24:25]
	v_mad_i64_i32 v[118:119], s[24:25], v120, s3, v[106:107]
	v_sub_f32_e32 v110, 1.0, v110
	v_sub_f32_e32 v111, 1.0, v111
	v_sub_f32_e32 v112, 1.0, v112
	v_sub_f32_e32 v113, 1.0, v113
	v_sub_f32_e32 v108, 1.0, v108
	v_sub_f32_e32 v109, 1.0, v109
	v_cvt_pk_bf16_f32 v114, v110, v111
	v_cvt_pk_bf16_f32 v115, v112, v113
	v_cvt_pk_bf16_f32 v117, v108, v109

.LBB0_831:
	s_and_b64 vcc, exec, s[24:25]
	s_cbranch_vccz .LBB0_833
	s_nop 0
	v_add_f32_e32 v106, v102, v134
	v_mul_f32_e32 v106, 0xbfb8aa3b, v106
	v_add_f32_e32 v107, v103, v135
	v_exp_f32_e32 v106, v106
	v_mul_f32_e32 v107, 0xbfb8aa3b, v107
	v_exp_f32_e32 v107, v107
	v_add_f32_e32 v108, v105, v137
	v_add_f32_e32 v106, 1.0, v106
	v_rcp_f32_e32 v113, v106
	v_add_f32_e32 v106, 1.0, v107
	v_add_f32_e32 v107, v104, v136
	v_mul_f32_e32 v107, 0xbfb8aa3b, v107
	v_exp_f32_e32 v107, v107
	v_mul_f32_e32 v108, 0xbfb8aa3b, v108
	v_exp_f32_e32 v108, v108
	v_rcp_f32_e32 v114, v106
	v_add_f32_e32 v106, 1.0, v107
	v_add_f32_e32 v107, v98, v126
	v_rcp_f32_e32 v115, v106
	v_add_f32_e32 v106, 1.0, v108
	v_mul_f32_e32 v107, 0xbfb8aa3b, v107
	v_add_f32_e32 v108, v99, v127
	v_exp_f32_e32 v107, v107
	v_mul_f32_e32 v108, 0xbfb8aa3b, v108
	v_exp_f32_e32 v108, v108
	v_rcp_f32_e32 v116, v106
	v_add_f32_e32 v106, 1.0, v107
	v_add_f32_e32 v107, v100, v128
	v_rcp_f32_e32 v117, v106
	v_add_f32_e32 v106, 1.0, v108
	v_mul_f32_e32 v107, 0xbfb8aa3b, v107
	v_add_f32_e32 v108, v101, v129
	v_exp_f32_e32 v107, v107
	v_mul_f32_e32 v108, 0xbfb8aa3b, v108
	v_exp_f32_e32 v108, v108
	v_rcp_f32_e32 v118, v106
	v_add_f32_e32 v106, 1.0, v107
	v_rcp_f32_e32 v119, v106
	v_add_f32_e32 v106, 1.0, v108
	v_rcp_f32_e32 v120, v106
	v_lshlrev_b32_e32 v106, 16, v46
	v_and_b32_e32 v107, 0xffff0000, v46
	v_lshlrev_b32_e32 v108, 16, v47
	v_lshlrev_b32_e32 v110, 16, v48
	v_and_b32_e32 v111, 0xffff0000, v48
	s_add_u32 s24, s18, s56
	v_and_b32_e32 v109, 0xffff0000, v47
	v_mul_f32_e32 v106, v113, v106
	v_mul_f32_e32 v107, v114, v107
	v_mul_f32_e32 v108, v115, v108
	v_mul_f32_e32 v110, v117, v110
	v_mul_f32_e32 v111, v118, v111
	s_addc_u32 s25, s19, s77
	v_mul_f32_e32 v109, v116, v109
	v_cvt_pk_bf16_f32 v106, v106, v107
	v_cvt_pk_bf16_f32 v107, v108, v109
	v_cvt_pk_bf16_f32 v108, v110, v111
	v_mov_b64_e32 v[110:111], s[24:25]
	v_mad_i64_i32 v[110:111], s[24:25], v112, s3, v[110:111]
	v_lshlrev_b32_e32 v121, 16, v49
	v_and_b32_e32 v122, 0xffff0000, v49
	v_lshl_add_u64 v[110:111], v[198:199], 1, v[110:111]
	v_add_f32_e32 v113, -1.0, v113
	v_mul_f32_e32 v121, v119, v121
	v_mul_f32_e32 v122, v120, v122
	v_cvt_pk_bf16_f32 v109, v121, v122
	global_store_dwordx4 v[110:111], v[106:109], off
	v_fma_f32 v113, v142, v113, 1.0
	v_lshlrev_b32_e32 v110, 16, v44
	v_lshlrev_b32_e32 v106, 16, v42
	v_mul_f32_e32 v106, v113, v106
	v_add_f32_e32 v113, -1.0, v114
	v_and_b32_e32 v107, 0xffff0000, v42
	v_fma_f32 v113, v143, v113, 1.0
	v_mul_f32_e32 v107, v113, v107
	v_add_f32_e32 v113, -1.0, v115
	v_lshlrev_b32_e32 v108, 16, v43
	v_fma_f32 v113, v144, v113, 1.0
	v_mul_f32_e32 v108, v113, v108
	v_add_f32_e32 v113, -1.0, v116
	v_and_b32_e32 v109, 0xffff0000, v43
	v_fma_f32 v113, v145, v113, 1.0
	v_mul_f32_e32 v109, v113, v109
	v_add_f32_e32 v113, -1.0, v117
	v_fma_f32 v113, v138, v113, 1.0
	v_mul_f32_e32 v110, v113, v110
	v_add_f32_e32 v113, -1.0, v118
	v_and_b32_e32 v111, 0xffff0000, v44
	v_fma_f32 v113, v139, v113, 1.0
	s_add_u32 s24, s18, s76
	v_mul_f32_e32 v111, v113, v111
	s_addc_u32 s25, s19, s86
	v_add_f32_e32 v113, -1.0, v119
	v_add_f32_e32 v114, -1.0, v120
	v_cvt_pk_bf16_f32 v106, v106, v107
	v_cvt_pk_bf16_f32 v107, v108, v109
	v_cvt_pk_bf16_f32 v108, v110, v111
	v_mov_b64_e32 v[110:111], s[24:25]
	v_lshlrev_b32_e32 v121, 16, v45
	v_and_b32_e32 v122, 0xffff0000, v45
	v_fma_f32 v113, v140, v113, 1.0
	v_fma_f32 v114, v141, v114, 1.0
	v_mad_i64_i32 v[110:111], s[24:25], v112, s3, v[110:111]
	v_mul_f32_e32 v113, v113, v121
	v_mul_f32_e32 v114, v114, v122
	v_cvt_pk_bf16_f32 v109, v113, v114

.LBB0_834:
	s_andn2_b64 vcc, exec, s[24:25]
	s_cbranch_vccnz .LBB0_836
	s_nop 0
	v_add_f32_e32 v98, v98, v126
	v_add_f32_e32 v99, v99, v127
	v_mul_f32_e32 v98, 0xbfb8aa3b, v98
	v_mul_f32_e32 v99, 0xbfb8aa3b, v99
	v_exp_f32_e32 v98, v98
	v_exp_f32_e32 v99, v99
	v_add_f32_e32 v102, v102, v134
	v_add_f32_e32 v103, v103, v135
	v_add_f32_e32 v104, v104, v136
	v_add_f32_e32 v105, v105, v137
	v_add_f32_e32 v100, v100, v128
	v_add_f32_e32 v101, v101, v129
	v_mul_f32_e32 v102, 0xbfb8aa3b, v102
	v_mul_f32_e32 v103, 0xbfb8aa3b, v103
	v_mul_f32_e32 v104, 0xbfb8aa3b, v104
	v_mul_f32_e32 v105, 0xbfb8aa3b, v105
	v_mul_f32_e32 v100, 0xbfb8aa3b, v100
	v_mul_f32_e32 v101, 0xbfb8aa3b, v101
	v_exp_f32_e32 v102, v102
	v_exp_f32_e32 v103, v103
	v_exp_f32_e32 v104, v104
	v_exp_f32_e32 v105, v105
	v_exp_f32_e32 v100, v100
	v_exp_f32_e32 v101, v101
	v_add_f32_e32 v98, 1.0, v98
	v_add_f32_e32 v99, 1.0, v99
	v_rcp_f32_e32 v98, v98
	v_rcp_f32_e32 v99, v99
	v_add_f32_e32 v102, 1.0, v102
	v_add_f32_e32 v103, 1.0, v103
	v_add_f32_e32 v104, 1.0, v104
	v_add_f32_e32 v105, 1.0, v105
	v_add_f32_e32 v100, 1.0, v100
	v_add_f32_e32 v101, 1.0, v101
	v_rcp_f32_e32 v102, v102
	v_rcp_f32_e32 v103, v103
	v_rcp_f32_e32 v104, v104
	v_rcp_f32_e32 v105, v105
	v_rcp_f32_e32 v100, v100
	v_rcp_f32_e32 v101, v101
	v_mul_f32_e32 v98, 0xbf1b4598, v98
	v_mul_f32_e32 v99, 0xbf1b4598, v99
	v_mul_f32_e32 v98, 0x3fb8aa3b, v98
	v_mul_f32_e32 v99, 0x3fb8aa3b, v99
	v_exp_f32_e32 v98, v98
	v_exp_f32_e32 v99, v99
	v_mul_f32_e32 v102, 0xbf1b4598, v102
	v_mul_f32_e32 v103, 0xbf1b4598, v103
	v_mul_f32_e32 v104, 0xbf1b4598, v104
	v_mul_f32_e32 v105, 0xbf1b4598, v105
	v_mul_f32_e32 v100, 0xbf1b4598, v100
	v_mul_f32_e32 v101, 0xbf1b4598, v101
	v_mul_f32_e32 v102, 0x3fb8aa3b, v102
	v_mul_f32_e32 v103, 0x3fb8aa3b, v103
	v_mul_f32_e32 v104, 0x3fb8aa3b, v104
	v_mul_f32_e32 v105, 0x3fb8aa3b, v105
	v_mul_f32_e32 v100, 0x3fb8aa3b, v100
	v_mul_f32_e32 v101, 0x3fb8aa3b, v101
	v_exp_f32_e32 v102, v102
	v_exp_f32_e32 v103, v103
	v_exp_f32_e32 v104, v104
	v_exp_f32_e32 v105, v105
	v_exp_f32_e32 v100, v100
	v_exp_f32_e32 v101, v101
	s_add_u32 s24, s18, s54
	v_sub_f32_e32 v98, 1.0, v98
	v_sub_f32_e32 v99, 1.0, v99
	s_addc_u32 s25, s19, s57
	v_cvt_pk_bf16_f32 v108, v98, v99
	v_mov_b64_e32 v[98:99], s[24:25]
	v_mad_i64_i32 v[110:111], s[24:25], v112, s3, v[98:99]
	v_sub_f32_e32 v102, 1.0, v102
	v_sub_f32_e32 v103, 1.0, v103
	v_sub_f32_e32 v104, 1.0, v104
	v_sub_f32_e32 v105, 1.0, v105
	v_sub_f32_e32 v100, 1.0, v100
	v_sub_f32_e32 v101, 1.0, v101
	v_cvt_pk_bf16_f32 v106, v102, v103
	v_cvt_pk_bf16_f32 v107, v104, v105
	v_cvt_pk_bf16_f32 v109, v100, v101

.LBB0_847:
	s_and_b64 vcc, exec, s[24:25]
	s_cbranch_vccz .LBB0_849
	v_add_f32_e32 v26, v22, v102
	v_mul_f32_e32 v26, 0xbfb8aa3b, v26
	v_add_f32_e32 v27, v23, v103
	v_exp_f32_e32 v26, v26
	v_mul_f32_e32 v27, 0xbfb8aa3b, v27
	v_exp_f32_e32 v27, v27
	v_add_f32_e32 v28, v25, v105
	v_add_f32_e32 v26, 1.0, v26
	v_rcp_f32_e32 v32, v26
	v_add_f32_e32 v26, 1.0, v27
	v_add_f32_e32 v27, v24, v104
	v_mul_f32_e32 v27, 0xbfb8aa3b, v27
	v_exp_f32_e32 v27, v27
	v_mul_f32_e32 v28, 0xbfb8aa3b, v28
	v_exp_f32_e32 v28, v28
	v_rcp_f32_e32 v33, v26
	v_add_f32_e32 v26, 1.0, v27
	v_add_f32_e32 v27, v18, v98
	v_rcp_f32_e32 v34, v26
	v_add_f32_e32 v26, 1.0, v28
	v_mul_f32_e32 v27, 0xbfb8aa3b, v27
	v_add_f32_e32 v28, v19, v99
	v_exp_f32_e32 v27, v27
	v_mul_f32_e32 v28, 0xbfb8aa3b, v28
	v_exp_f32_e32 v28, v28
	v_rcp_f32_e32 v35, v26
	v_add_f32_e32 v26, 1.0, v27
	v_add_f32_e32 v27, v20, v100
	v_rcp_f32_e32 v36, v26
	v_add_f32_e32 v26, 1.0, v28
	v_mul_f32_e32 v27, 0xbfb8aa3b, v27
	v_add_f32_e32 v28, v21, v101
	v_exp_f32_e32 v27, v27
	v_mul_f32_e32 v28, 0xbfb8aa3b, v28
	v_exp_f32_e32 v28, v28
	v_rcp_f32_e32 v37, v26
	v_add_f32_e32 v26, 1.0, v27
	v_rcp_f32_e32 v38, v26
	v_add_f32_e32 v26, 1.0, v28
	v_rcp_f32_e32 v39, v26
	s_nop 0
	v_lshlrev_b32_e32 v26, 16, v74
	v_and_b32_e32 v27, 0xffff0000, v74
	v_lshlrev_b32_e32 v28, 16, v75
	v_lshlrev_b32_e32 v30, 16, v76
	v_and_b32_e32 v31, 0xffff0000, v76
	s_add_u32 s24, s18, s57
	v_and_b32_e32 v29, 0xffff0000, v75
	v_mul_f32_e32 v26, v32, v26
	v_mul_f32_e32 v27, v33, v27
	v_mul_f32_e32 v28, v34, v28
	v_mul_f32_e32 v30, v36, v30
	v_mul_f32_e32 v31, v37, v31
	s_addc_u32 s25, s19, s56
	v_mul_f32_e32 v29, v35, v29
	v_cvt_pk_bf16_f32 v26, v26, v27
	v_cvt_pk_bf16_f32 v27, v28, v29
	v_cvt_pk_bf16_f32 v28, v30, v31
	v_mov_b64_e32 v[30:31], s[24:25]
	v_mad_i64_i32 v[30:31], s[24:25], v50, s3, v[30:31]
	v_lshlrev_b32_e32 v51, 16, v77
	v_and_b32_e32 v52, 0xffff0000, v77
	v_lshl_add_u64 v[30:31], v[118:119], 1, v[30:31]
	v_add_f32_e32 v32, -1.0, v32
	v_mul_f32_e32 v51, v38, v51
	v_mul_f32_e32 v52, v39, v52
	v_cvt_pk_bf16_f32 v29, v51, v52
	global_store_dwordx4 v[30:31], v[26:29], off
	v_fma_f32 v32, v110, v32, 1.0
	v_lshlrev_b32_e32 v30, 16, v72
	v_lshlrev_b32_e32 v26, 16, v70
	v_mul_f32_e32 v26, v32, v26
	v_add_f32_e32 v32, -1.0, v33
	v_and_b32_e32 v27, 0xffff0000, v70
	v_fma_f32 v32, v111, v32, 1.0
	v_mul_f32_e32 v27, v32, v27
	v_add_f32_e32 v32, -1.0, v34
	v_lshlrev_b32_e32 v28, 16, v71
	v_fma_f32 v32, v112, v32, 1.0
	v_mul_f32_e32 v28, v32, v28
	v_add_f32_e32 v32, -1.0, v35
	v_and_b32_e32 v29, 0xffff0000, v71
	v_fma_f32 v32, v113, v32, 1.0
	v_mul_f32_e32 v29, v32, v29
	v_add_f32_e32 v32, -1.0, v36
	v_fma_f32 v32, v106, v32, 1.0
	v_mul_f32_e32 v30, v32, v30
	v_add_f32_e32 v32, -1.0, v37
	v_and_b32_e32 v31, 0xffff0000, v72
	v_fma_f32 v32, v107, v32, 1.0
	s_add_u32 s24, s18, s86
	v_mul_f32_e32 v31, v32, v31
	s_addc_u32 s25, s19, s76
	v_add_f32_e32 v32, -1.0, v38
	v_add_f32_e32 v33, -1.0, v39
	v_cvt_pk_bf16_f32 v26, v26, v27
	v_cvt_pk_bf16_f32 v27, v28, v29
	v_cvt_pk_bf16_f32 v28, v30, v31
	v_mov_b64_e32 v[30:31], s[24:25]
	v_lshlrev_b32_e32 v51, 16, v73
	v_and_b32_e32 v52, 0xffff0000, v73
	v_fma_f32 v32, v108, v32, 1.0
	v_fma_f32 v33, v109, v33, 1.0
	v_mad_i64_i32 v[30:31], s[24:25], v50, s3, v[30:31]
	v_mul_f32_e32 v32, v32, v51
	v_mul_f32_e32 v33, v33, v52
	v_cvt_pk_bf16_f32 v29, v32, v33

.LBB0_859:
	s_and_b64 vcc, exec, s[24:25]
	s_cbranch_vccz .LBB0_861
	v_add_f32_e32 v18, v14, v102
	v_mul_f32_e32 v18, 0xbfb8aa3b, v18
	v_add_f32_e32 v19, v15, v103
	v_exp_f32_e32 v18, v18
	v_mul_f32_e32 v19, 0xbfb8aa3b, v19
	v_exp_f32_e32 v19, v19
	v_add_f32_e32 v20, v17, v105
	v_add_f32_e32 v18, 1.0, v18
	v_rcp_f32_e32 v24, v18
	v_add_f32_e32 v18, 1.0, v19
	v_add_f32_e32 v19, v16, v104
	v_mul_f32_e32 v19, 0xbfb8aa3b, v19
	v_exp_f32_e32 v19, v19
	v_mul_f32_e32 v20, 0xbfb8aa3b, v20
	v_exp_f32_e32 v20, v20
	v_rcp_f32_e32 v25, v18
	v_add_f32_e32 v18, 1.0, v19
	v_add_f32_e32 v19, v10, v98
	v_rcp_f32_e32 v26, v18
	v_add_f32_e32 v18, 1.0, v20
	v_mul_f32_e32 v19, 0xbfb8aa3b, v19
	v_add_f32_e32 v20, v11, v99
	v_exp_f32_e32 v19, v19
	v_mul_f32_e32 v20, 0xbfb8aa3b, v20
	v_exp_f32_e32 v20, v20
	v_rcp_f32_e32 v27, v18
	v_add_f32_e32 v18, 1.0, v19
	v_add_f32_e32 v19, v12, v100
	v_rcp_f32_e32 v28, v18
	v_add_f32_e32 v18, 1.0, v20
	v_mul_f32_e32 v19, 0xbfb8aa3b, v19
	v_add_f32_e32 v20, v13, v101
	v_exp_f32_e32 v19, v19
	v_mul_f32_e32 v20, 0xbfb8aa3b, v20
	v_exp_f32_e32 v20, v20
	v_rcp_f32_e32 v29, v18
	v_add_f32_e32 v18, 1.0, v19
	v_rcp_f32_e32 v30, v18
	v_add_f32_e32 v18, 1.0, v20
	v_rcp_f32_e32 v31, v18
	s_nop 0
	v_lshlrev_b32_e32 v18, 16, v62
	v_and_b32_e32 v19, 0xffff0000, v62
	v_lshlrev_b32_e32 v20, 16, v63
	v_lshlrev_b32_e32 v22, 16, v64
	v_and_b32_e32 v23, 0xffff0000, v64
	s_add_u32 s24, s18, s57
	v_and_b32_e32 v21, 0xffff0000, v63
	v_mul_f32_e32 v18, v24, v18
	v_mul_f32_e32 v19, v25, v19
	v_mul_f32_e32 v20, v26, v20
	v_mul_f32_e32 v22, v28, v22
	v_mul_f32_e32 v23, v29, v23
	s_addc_u32 s25, s19, s56
	v_mul_f32_e32 v21, v27, v21
	v_cvt_pk_bf16_f32 v18, v18, v19
	v_cvt_pk_bf16_f32 v19, v20, v21
	v_cvt_pk_bf16_f32 v20, v22, v23
	v_mov_b64_e32 v[22:23], s[24:25]
	v_mad_i64_i32 v[22:23], s[24:25], v41, s3, v[22:23]
	v_lshlrev_b32_e32 v32, 16, v65
	v_and_b32_e32 v33, 0xffff0000, v65
	v_lshl_add_u64 v[22:23], v[118:119], 1, v[22:23]
	v_add_f32_e32 v24, -1.0, v24
	v_mul_f32_e32 v32, v30, v32
	v_mul_f32_e32 v33, v31, v33
	v_cvt_pk_bf16_f32 v21, v32, v33
	global_store_dwordx4 v[22:23], v[18:21], off
	v_fma_f32 v24, v110, v24, 1.0
	v_lshlrev_b32_e32 v22, 16, v56
	v_lshlrev_b32_e32 v18, 16, v54
	v_mul_f32_e32 v18, v24, v18
	v_add_f32_e32 v24, -1.0, v25
	v_and_b32_e32 v19, 0xffff0000, v54
	v_fma_f32 v24, v111, v24, 1.0
	v_mul_f32_e32 v19, v24, v19
	v_add_f32_e32 v24, -1.0, v26
	v_lshlrev_b32_e32 v20, 16, v55
	v_fma_f32 v24, v112, v24, 1.0
	v_mul_f32_e32 v20, v24, v20
	v_add_f32_e32 v24, -1.0, v27
	v_and_b32_e32 v21, 0xffff0000, v55
	v_fma_f32 v24, v113, v24, 1.0
	v_mul_f32_e32 v21, v24, v21
	v_add_f32_e32 v24, -1.0, v28
	v_fma_f32 v24, v106, v24, 1.0
	v_mul_f32_e32 v22, v24, v22
	v_add_f32_e32 v24, -1.0, v29
	v_and_b32_e32 v23, 0xffff0000, v56
	v_fma_f32 v24, v107, v24, 1.0
	s_add_u32 s24, s18, s86
	v_mul_f32_e32 v23, v24, v23
	s_addc_u32 s25, s19, s76
	v_add_f32_e32 v24, -1.0, v30
	v_add_f32_e32 v25, -1.0, v31
	v_cvt_pk_bf16_f32 v18, v18, v19
	v_cvt_pk_bf16_f32 v19, v20, v21
	v_cvt_pk_bf16_f32 v20, v22, v23
	v_mov_b64_e32 v[22:23], s[24:25]
	v_lshlrev_b32_e32 v32, 16, v57
	v_and_b32_e32 v33, 0xffff0000, v57
	v_fma_f32 v24, v108, v24, 1.0
	v_fma_f32 v25, v109, v25, 1.0
	v_mad_i64_i32 v[22:23], s[24:25], v41, s3, v[22:23]
	v_mul_f32_e32 v24, v24, v32
	v_mul_f32_e32 v25, v25, v33
	v_cvt_pk_bf16_f32 v21, v24, v25

.LBB0_871:
	s_and_b64 vcc, exec, s[24:25]
	s_cbranch_vccz .LBB0_873
	v_add_f32_e32 v10, v6, v102
	v_mul_f32_e32 v10, 0xbfb8aa3b, v10
	v_add_f32_e32 v11, v7, v103
	v_exp_f32_e32 v10, v10
	v_mul_f32_e32 v11, 0xbfb8aa3b, v11
	v_exp_f32_e32 v11, v11
	v_add_f32_e32 v12, v9, v105
	v_add_f32_e32 v10, 1.0, v10
	v_rcp_f32_e32 v16, v10
	v_add_f32_e32 v10, 1.0, v11
	v_add_f32_e32 v11, v8, v104
	v_mul_f32_e32 v11, 0xbfb8aa3b, v11
	v_exp_f32_e32 v11, v11
	v_mul_f32_e32 v12, 0xbfb8aa3b, v12
	v_exp_f32_e32 v12, v12
	v_rcp_f32_e32 v17, v10
	v_add_f32_e32 v10, 1.0, v11
	v_add_f32_e32 v11, v2, v98
	v_rcp_f32_e32 v18, v10
	v_add_f32_e32 v10, 1.0, v12
	v_mul_f32_e32 v11, 0xbfb8aa3b, v11
	v_add_f32_e32 v12, v3, v99
	v_exp_f32_e32 v11, v11
	v_mul_f32_e32 v12, 0xbfb8aa3b, v12
	v_exp_f32_e32 v12, v12
	v_rcp_f32_e32 v19, v10
	v_add_f32_e32 v10, 1.0, v11
	v_add_f32_e32 v11, v4, v100
	v_rcp_f32_e32 v20, v10
	v_add_f32_e32 v10, 1.0, v12
	v_mul_f32_e32 v11, 0xbfb8aa3b, v11
	v_add_f32_e32 v12, v5, v101
	v_exp_f32_e32 v11, v11
	v_mul_f32_e32 v12, 0xbfb8aa3b, v12
	v_exp_f32_e32 v12, v12
	v_rcp_f32_e32 v21, v10
	v_add_f32_e32 v10, 1.0, v11
	v_rcp_f32_e32 v22, v10
	v_add_f32_e32 v10, 1.0, v12
	v_rcp_f32_e32 v23, v10
	s_nop 0
	v_lshlrev_b32_e32 v10, 16, v46
	v_and_b32_e32 v11, 0xffff0000, v46
	v_lshlrev_b32_e32 v12, 16, v47
	v_lshlrev_b32_e32 v14, 16, v48
	v_and_b32_e32 v15, 0xffff0000, v48
	s_add_u32 s24, s18, s57
	v_and_b32_e32 v13, 0xffff0000, v47
	v_mul_f32_e32 v10, v16, v10
	v_mul_f32_e32 v11, v17, v11
	v_mul_f32_e32 v12, v18, v12
	v_mul_f32_e32 v14, v20, v14
	v_mul_f32_e32 v15, v21, v15
	s_addc_u32 s25, s19, s56
	v_mul_f32_e32 v13, v19, v13
	v_cvt_pk_bf16_f32 v10, v10, v11
	v_cvt_pk_bf16_f32 v11, v12, v13
	v_cvt_pk_bf16_f32 v12, v14, v15
	v_mov_b64_e32 v[14:15], s[24:25]
	v_mad_i64_i32 v[14:15], s[24:25], v40, s3, v[14:15]
	v_lshlrev_b32_e32 v24, 16, v49
	v_and_b32_e32 v25, 0xffff0000, v49
	v_lshl_add_u64 v[14:15], v[118:119], 1, v[14:15]
	v_add_f32_e32 v16, -1.0, v16
	v_mul_f32_e32 v24, v22, v24
	v_mul_f32_e32 v25, v23, v25
	v_cvt_pk_bf16_f32 v13, v24, v25
	global_store_dwordx4 v[14:15], v[10:13], off
	v_fma_f32 v16, v110, v16, 1.0
	v_lshlrev_b32_e32 v14, 16, v44
	v_lshlrev_b32_e32 v10, 16, v42
	v_mul_f32_e32 v10, v16, v10
	v_add_f32_e32 v16, -1.0, v17
	v_and_b32_e32 v11, 0xffff0000, v42
	v_fma_f32 v16, v111, v16, 1.0
	v_mul_f32_e32 v11, v16, v11
	v_add_f32_e32 v16, -1.0, v18
	v_lshlrev_b32_e32 v12, 16, v43
	v_fma_f32 v16, v112, v16, 1.0
	v_mul_f32_e32 v12, v16, v12
	v_add_f32_e32 v16, -1.0, v19
	v_and_b32_e32 v13, 0xffff0000, v43
	v_fma_f32 v16, v113, v16, 1.0
	v_mul_f32_e32 v13, v16, v13
	v_add_f32_e32 v16, -1.0, v20
	v_fma_f32 v16, v106, v16, 1.0
	v_mul_f32_e32 v14, v16, v14
	v_add_f32_e32 v16, -1.0, v21
	v_and_b32_e32 v15, 0xffff0000, v44
	v_fma_f32 v16, v107, v16, 1.0
	s_add_u32 s24, s18, s86
	v_mul_f32_e32 v15, v16, v15
	s_addc_u32 s25, s19, s76
	v_add_f32_e32 v16, -1.0, v22
	v_add_f32_e32 v17, -1.0, v23
	v_cvt_pk_bf16_f32 v10, v10, v11
	v_cvt_pk_bf16_f32 v11, v12, v13
	v_cvt_pk_bf16_f32 v12, v14, v15
	v_mov_b64_e32 v[14:15], s[24:25]
	v_lshlrev_b32_e32 v24, 16, v45
	v_and_b32_e32 v25, 0xffff0000, v45
	v_fma_f32 v16, v108, v16, 1.0
	v_fma_f32 v17, v109, v17, 1.0
	v_mad_i64_i32 v[14:15], s[24:25], v40, s3, v[14:15]
	v_mul_f32_e32 v16, v16, v24
	v_mul_f32_e32 v17, v17, v25
	v_cvt_pk_bf16_f32 v13, v16, v17

.LBB0_1036:
	s_waitcnt lgkmcnt(0)
	s_barrier
	s_and_saveexec_b64 s[24:25], s[42:43]
	s_movk_i32 s28, 0xfe80
	s_cbranch_execz .LBB0_886
	s_ashr_i32 s26, s13, 31
	s_add_u32 s44, s56, s13
	s_addc_u32 s45, s57, s26
	s_mov_b64 s[46:47], 0
	s_nop 0
	v_mov_b32_e32 v2, v49
	v_mov_b32_e32 v0, v48
	v_mov_b32_e32 v3, v47
.LBB0_1038:
	v_mul_hi_i32 v4, v3, s11
	v_lshrrev_b32_e32 v5, 31, v4
	v_add_u32_e32 v20, v4, v5
	v_mad_u64_u32 v[22:23], s[26:27], v20, s28, v[0:1]
	v_ashrrev_i32_e32 v23, 31, v22
	v_lshl_add_u64 v[16:17], v[22:23], 2, s[54:55]
	s_nop 0
	ds_read_b128 v[4:7], v2
	s_nop 0
	ds_read_b128 v[8:11], v2 offset:16
	global_load_dwordx4 v[12:15], v[16:17], off offset:16
	s_nop 0
	global_load_dwordx4 v[16:19], v[16:17], off
	v_ashrrev_i32_e32 v21, 31, v20
	v_add_u32_e32 v0, 0x1000, v0
	v_add_u32_e32 v2, 0x4000, v2
	s_waitcnt vmcnt(1) lgkmcnt(0)
	v_pk_mul_f32 v[8:9], v[8:9], v[12:13]
	s_waitcnt vmcnt(0)
	v_pk_mul_f32 v[4:5], v[4:5], v[16:17]
	v_pk_mul_f32 v[6:7], v[6:7], v[18:19]
	v_pk_mul_f32 v[16:17], v[4:5], v[4:5]
	v_pk_mul_f32 v[18:19], v[6:7], v[6:7]
	v_add_f32_e32 v16, v16, v17
	v_add_f32_e32 v16, v16, v18
	v_pk_mul_f32 v[12:13], v[8:9], v[8:9]
	v_add_f32_e32 v16, v16, v19
	v_pk_mul_f32 v[10:11], v[10:11], v[14:15]
	v_add_f32_e32 v12, v16, v12
	v_pk_mul_f32 v[14:15], v[10:11], v[10:11]
	v_add_f32_e32 v12, v12, v13
	v_add_f32_e32 v12, v12, v14
	v_add_f32_e32 v12, v12, v15
	s_nop 1
	v_add_f32_dpp v12, v12, v12 quad_perm:[1,0,3,2] row_mask:0xf bank_mask:0xf bound_ctrl:1
	s_nop 1
	v_add_f32_dpp v12, v12, v12 quad_perm:[2,3,0,1] row_mask:0xf bank_mask:0xf bound_ctrl:1
	s_nop 1
	v_add_f32_dpp v12, v12, v12 row_half_mirror row_mask:0xf bank_mask:0xf bound_ctrl:1
	v_add_f32_e32 v12, 0x2b8cbccc, v12
	v_cmp_gt_f32_e32 vcc, s66, v12
	v_mul_f32_e32 v13, 0x4b800000, v12
	s_nop 0
	v_cndmask_b32_e32 v12, v12, v13, vcc
	v_rsq_f32_e32 v12, v12
	s_nop 0
	v_mul_f32_e32 v13, 0x45800000, v12
	v_cndmask_b32_e32 v12, v12, v13, vcc
	v_mul_f32_e32 v4, v4, v12
	v_mul_f32_e32 v5, v5, v12
	v_mul_f32_e32 v6, v6, v12
	v_mul_f32_e32 v7, v7, v12
	v_mul_f32_e32 v8, v8, v12
	v_mul_f32_e32 v9, v9, v12
	v_mul_f32_e32 v10, v10, v12
	v_mul_f32_e32 v11, v11, v12
	v_cvt_pk_bf16_f32 v4, v4, v5
	v_cvt_pk_bf16_f32 v5, v6, v7
	v_cvt_pk_bf16_f32 v6, v8, v9
	v_cvt_pk_bf16_f32 v7, v10, v11
	v_lshl_add_u64 v[8:9], s[44:45], 0, v[20:21]
	v_mov_b64_e32 v[10:11], s[22:23]
	v_mad_u64_u32 v[10:11], s[26:27], v8, s3, v[10:11]
	v_mov_b32_e32 v8, v11
	v_mad_u64_u32 v[8:9], s[26:27], v9, s3, v[8:9]
	v_mov_b32_e32 v11, v8
	v_lshl_add_u64 v[8:9], v[22:23], 1, v[10:11]
	global_store_dwordx4 v[8:9], v[4:7], off
	v_cmp_lt_i32_e32 vcc, 31, v3
	s_or_b64 s[46:47], vcc, s[46:47]
	v_add_u32_e32 v4, 64, v3
	v_mov_b32_e32 v3, v4
	s_andn2_b64 exec, exec, s[46:47]
	s_cbranch_execnz .LBB0_1038
	s_branch .LBB0_886
